# back-edge rotation (asm guide 7.11) in the five big K-loops: counter/test/branch before the loop-closing barrier, on top of v45
# baseline (speedup 1.0000x reference)
.LBB0_232:
	s_lshl_b32 s53, s52, 19
	s_add_i32 s53, s53, 0x4000000
	s_and_b64 s[18:19], s[2:3], exec
	s_cselect_b32 s18, s53, s58
	s_lshl_b32 s54, s51, 19
	s_add_i32 s54, s54, 0x900000
	s_and_b64 s[60:61], s[2:3], exec
	s_cselect_b32 s19, s54, s57
	s_add_i32 s33, s58, 0x2180
	s_addk_i32 s57, 0x200
	s_mov_b32 s58, 0
	s_branch .LBB0_233
my_rot_233:
	s_barrier
.LBB0_233:
	ds_read_b128 v[130:133], v213
	ds_read_b128 v[134:137], v214
	ds_read_b128 v[138:141], v215
	ds_read_b128 v[142:145], v216
	ds_read_b128 v[146:149], v217
	ds_read_b128 v[150:153], v218
	ds_read_b128 v[154:157], v219
	ds_read_b128 v[158:161], v220
	s_add_i32 s4, s33, 0xffffe080
	s_cmp_eq_u32 s58, 12
	s_cselect_b32 s61, s18, s4
	s_cselect_b32 s60, s19, s57
	s_add_i32 s59, s61, 0x80
	s_mov_b32 s4, s70
	s_mov_b32 m0, s38
	ds_read_b128 v[162:165], v221
	ds_read_b128 v[166:169], v221 offset:2048
	ds_read_b128 v[170:173], v222
	ds_read_b128 v[174:177], v222 offset:2048
	ds_read_b128 v[178:181], v221 offset:4096
	ds_read_b128 v[182:185], v221 offset:6144
	ds_read_b128 v[186:189], v222 offset:4096
	ds_read_b128 v[190:193], v222 offset:6144
	buffer_load_dwordx4 v207, s[4:7], s33 offen lds
	s_mov_b32 m0, s41
	s_nop 0
	buffer_load_dwordx4 v209, s[4:7], s33 offen lds
	s_waitcnt vmcnt(8)
	s_waitcnt lgkmcnt(0)
	s_barrier
	s_setprio 1
	s_waitcnt lgkmcnt(7)
	v_mfma_f32_16x16x32_bf16 v[114:117], v[130:133], v[162:165], v[114:117]
	v_mfma_f32_16x16x32_bf16 v[110:113], v[138:141], v[162:165], v[110:113]
	s_waitcnt lgkmcnt(6)
	v_mfma_f32_16x16x32_bf16 v[106:109], v[130:133], v[166:169], v[106:109]
	v_mfma_f32_16x16x32_bf16 v[102:105], v[138:141], v[166:169], v[102:105]
	s_waitcnt lgkmcnt(3)
	v_mfma_f32_16x16x32_bf16 v[98:101], v[130:133], v[178:181], v[98:101]
	v_mfma_f32_16x16x32_bf16 v[94:97], v[138:141], v[178:181], v[94:97]
	s_waitcnt lgkmcnt(2)
	v_mfma_f32_16x16x32_bf16 v[90:93], v[130:133], v[182:185], v[90:93]
	v_mfma_f32_16x16x32_bf16 v[86:89], v[138:141], v[182:185], v[86:89]
	v_mfma_f32_16x16x32_bf16 v[114:117], v[134:137], v[170:173], v[114:117]
	v_mfma_f32_16x16x32_bf16 v[110:113], v[142:145], v[170:173], v[110:113]
	v_mfma_f32_16x16x32_bf16 v[106:109], v[134:137], v[174:177], v[106:109]
	v_mfma_f32_16x16x32_bf16 v[102:105], v[142:145], v[174:177], v[102:105]
	s_waitcnt lgkmcnt(1)
	v_mfma_f32_16x16x32_bf16 v[98:101], v[134:137], v[186:189], v[98:101]
	v_mfma_f32_16x16x32_bf16 v[94:97], v[142:145], v[186:189], v[94:97]
	s_waitcnt lgkmcnt(0)
	v_mfma_f32_16x16x32_bf16 v[90:93], v[134:137], v[190:193], v[90:93]
	v_mfma_f32_16x16x32_bf16 v[86:89], v[142:145], v[190:193], v[86:89]
	s_setprio 0
	s_setprio 1
	v_mfma_f32_16x16x32_bf16 v[82:85], v[146:149], v[162:165], v[82:85]
	v_mfma_f32_16x16x32_bf16 v[74:77], v[154:157], v[162:165], v[74:77]
	v_mfma_f32_16x16x32_bf16 v[70:73], v[146:149], v[166:169], v[70:73]
	v_mfma_f32_16x16x32_bf16 v[66:69], v[154:157], v[166:169], v[66:69]
	v_mfma_f32_16x16x32_bf16 v[62:65], v[146:149], v[178:181], v[62:65]
	v_mfma_f32_16x16x32_bf16 v[58:61], v[154:157], v[178:181], v[58:61]
	v_mfma_f32_16x16x32_bf16 v[54:57], v[146:149], v[182:185], v[54:57]
	v_mfma_f32_16x16x32_bf16 v[50:53], v[154:157], v[182:185], v[50:53]
	v_mfma_f32_16x16x32_bf16 v[82:85], v[150:153], v[170:173], v[82:85]
	v_mfma_f32_16x16x32_bf16 v[74:77], v[158:161], v[170:173], v[74:77]
	v_mfma_f32_16x16x32_bf16 v[70:73], v[150:153], v[174:177], v[70:73]
	v_mfma_f32_16x16x32_bf16 v[66:69], v[158:161], v[174:177], v[66:69]
	v_mfma_f32_16x16x32_bf16 v[62:65], v[150:153], v[186:189], v[62:65]
	v_mfma_f32_16x16x32_bf16 v[58:61], v[158:161], v[186:189], v[58:61]
	v_mfma_f32_16x16x32_bf16 v[54:57], v[150:153], v[190:193], v[54:57]
	v_mfma_f32_16x16x32_bf16 v[50:53], v[158:161], v[190:193], v[50:53]
	s_setprio 0
	s_barrier
	s_mov_b32 m0, s21
	ds_read_b128 v[162:165], v221 offset:16384
	ds_read_b128 v[166:169], v221 offset:18432
	ds_read_b128 v[170:173], v222 offset:16384
	ds_read_b128 v[174:177], v222 offset:18432
	ds_read_b128 v[178:181], v221 offset:20480
	ds_read_b128 v[182:185], v221 offset:22528
	ds_read_b128 v[186:189], v222 offset:20480
	ds_read_b128 v[190:193], v222 offset:22528
	buffer_load_dwordx4 v208, s[4:7], s60 offen lds
	s_mov_b32 m0, s22
	s_add_i32 s62, s60, 0x40000
	buffer_load_dwordx4 v210, s[4:7], s60 offen lds
	s_mov_b32 m0, s23
	s_nop 0
	buffer_load_dwordx4 v208, s[4:7], s62 offen lds
	s_mov_b32 m0, s24
	s_nop 0
	buffer_load_dwordx4 v210, s[4:7], s62 offen lds
	s_mov_b32 m0, s20
	s_nop 0
	buffer_load_dwordx4 v207, s[4:7], s61 offen lds
	s_mov_b32 m0, s25
	s_nop 0
	buffer_load_dwordx4 v209, s[4:7], s61 offen lds
	s_waitcnt vmcnt(8)
	s_waitcnt lgkmcnt(0)
	s_barrier
	s_setprio 1
	s_waitcnt lgkmcnt(7)
	v_mfma_f32_16x16x32_bf16 v[78:81], v[130:133], v[162:165], v[78:81]
	v_mfma_f32_16x16x32_bf16 v[46:49], v[138:141], v[162:165], v[46:49]
	s_waitcnt lgkmcnt(6)
	v_mfma_f32_16x16x32_bf16 v[42:45], v[130:133], v[166:169], v[42:45]
	v_mfma_f32_16x16x32_bf16 v[38:41], v[138:141], v[166:169], v[38:41]
	s_waitcnt lgkmcnt(3)
	v_mfma_f32_16x16x32_bf16 v[34:37], v[130:133], v[178:181], v[34:37]
	v_mfma_f32_16x16x32_bf16 v[30:33], v[138:141], v[178:181], v[30:33]
	s_waitcnt lgkmcnt(2)
	v_mfma_f32_16x16x32_bf16 v[26:29], v[130:133], v[182:185], v[26:29]
	v_mfma_f32_16x16x32_bf16 v[22:25], v[138:141], v[182:185], v[22:25]
	v_mfma_f32_16x16x32_bf16 v[78:81], v[134:137], v[170:173], v[78:81]
	v_mfma_f32_16x16x32_bf16 v[46:49], v[142:145], v[170:173], v[46:49]
	v_mfma_f32_16x16x32_bf16 v[42:45], v[134:137], v[174:177], v[42:45]
	v_mfma_f32_16x16x32_bf16 v[38:41], v[142:145], v[174:177], v[38:41]
	s_waitcnt lgkmcnt(1)
	v_mfma_f32_16x16x32_bf16 v[34:37], v[134:137], v[186:189], v[34:37]
	v_mfma_f32_16x16x32_bf16 v[30:33], v[142:145], v[186:189], v[30:33]
	s_waitcnt lgkmcnt(0)
	v_mfma_f32_16x16x32_bf16 v[26:29], v[134:137], v[190:193], v[26:29]
	v_mfma_f32_16x16x32_bf16 v[22:25], v[142:145], v[190:193], v[22:25]
	s_setprio 0
	s_setprio 1
	v_mfma_f32_16x16x32_bf16 v[18:21], v[146:149], v[162:165], v[18:21]
	v_mfma_f32_16x16x32_bf16 v[14:17], v[154:157], v[162:165], v[14:17]
	v_mfma_f32_16x16x32_bf16 v[10:13], v[146:149], v[166:169], v[10:13]
	v_mfma_f32_16x16x32_bf16 v[6:9], v[154:157], v[166:169], v[6:9]
	v_mfma_f32_16x16x32_bf16 v[2:5], v[146:149], v[178:181], v[2:5]
	v_mfma_f32_16x16x32_bf16 v[126:129], v[154:157], v[178:181], v[126:129]
	v_mfma_f32_16x16x32_bf16 v[122:125], v[146:149], v[182:185], v[122:125]
	v_mfma_f32_16x16x32_bf16 v[118:121], v[154:157], v[182:185], v[118:121]
	v_mfma_f32_16x16x32_bf16 v[18:21], v[150:153], v[170:173], v[18:21]
	v_mfma_f32_16x16x32_bf16 v[14:17], v[158:161], v[170:173], v[14:17]
	v_mfma_f32_16x16x32_bf16 v[10:13], v[150:153], v[174:177], v[10:13]
	v_mfma_f32_16x16x32_bf16 v[6:9], v[158:161], v[174:177], v[6:9]
	v_mfma_f32_16x16x32_bf16 v[2:5], v[150:153], v[186:189], v[2:5]
	v_mfma_f32_16x16x32_bf16 v[126:129], v[158:161], v[186:189], v[126:129]
	v_mfma_f32_16x16x32_bf16 v[122:125], v[150:153], v[190:193], v[122:125]
	v_mfma_f32_16x16x32_bf16 v[118:121], v[158:161], v[190:193], v[118:121]
	s_setprio 0
	s_barrier
	ds_read_b128 v[130:133], v194
	ds_read_b128 v[134:137], v224
	ds_read_b128 v[138:141], v225
	ds_read_b128 v[142:145], v228
	ds_read_b128 v[146:149], v229
	ds_read_b128 v[150:153], v230
	ds_read_b128 v[154:157], v231
	ds_read_b128 v[158:161], v233
	s_addk_i32 s61, 0x2000
	s_mov_b32 m0, s26
	ds_read_b128 v[162:165], v221 offset:32768
	ds_read_b128 v[166:169], v221 offset:34816
	ds_read_b128 v[170:173], v222 offset:32768
	ds_read_b128 v[174:177], v222 offset:34816
	ds_read_b128 v[178:181], v221 offset:36864
	ds_read_b128 v[182:185], v221 offset:38912
	ds_read_b128 v[186:189], v222 offset:36864
	ds_read_b128 v[190:193], v222 offset:38912
	buffer_load_dwordx4 v207, s[4:7], s61 offen lds
	s_mov_b32 m0, s27
	s_nop 0
	buffer_load_dwordx4 v209, s[4:7], s61 offen lds
	s_waitcnt vmcnt(8)
	s_waitcnt lgkmcnt(0)
	s_barrier
	s_setprio 1
	s_waitcnt lgkmcnt(7)
	v_mfma_f32_16x16x32_bf16 v[114:117], v[130:133], v[162:165], v[114:117]
	v_mfma_f32_16x16x32_bf16 v[110:113], v[138:141], v[162:165], v[110:113]
	s_waitcnt lgkmcnt(6)
	v_mfma_f32_16x16x32_bf16 v[106:109], v[130:133], v[166:169], v[106:109]
	v_mfma_f32_16x16x32_bf16 v[102:105], v[138:141], v[166:169], v[102:105]
	s_waitcnt lgkmcnt(3)
	v_mfma_f32_16x16x32_bf16 v[98:101], v[130:133], v[178:181], v[98:101]
	v_mfma_f32_16x16x32_bf16 v[94:97], v[138:141], v[178:181], v[94:97]
	s_waitcnt lgkmcnt(2)
	v_mfma_f32_16x16x32_bf16 v[90:93], v[130:133], v[182:185], v[90:93]
	v_mfma_f32_16x16x32_bf16 v[86:89], v[138:141], v[182:185], v[86:89]
	v_mfma_f32_16x16x32_bf16 v[114:117], v[134:137], v[170:173], v[114:117]
	v_mfma_f32_16x16x32_bf16 v[110:113], v[142:145], v[170:173], v[110:113]
	v_mfma_f32_16x16x32_bf16 v[106:109], v[134:137], v[174:177], v[106:109]
	v_mfma_f32_16x16x32_bf16 v[102:105], v[142:145], v[174:177], v[102:105]
	s_waitcnt lgkmcnt(1)
	v_mfma_f32_16x16x32_bf16 v[98:101], v[134:137], v[186:189], v[98:101]
	v_mfma_f32_16x16x32_bf16 v[94:97], v[142:145], v[186:189], v[94:97]
	s_waitcnt lgkmcnt(0)
	v_mfma_f32_16x16x32_bf16 v[90:93], v[134:137], v[190:193], v[90:93]
	v_mfma_f32_16x16x32_bf16 v[86:89], v[142:145], v[190:193], v[86:89]
	s_setprio 0
	s_setprio 1
	v_mfma_f32_16x16x32_bf16 v[82:85], v[146:149], v[162:165], v[82:85]
	v_mfma_f32_16x16x32_bf16 v[74:77], v[154:157], v[162:165], v[74:77]
	v_mfma_f32_16x16x32_bf16 v[70:73], v[146:149], v[166:169], v[70:73]
	v_mfma_f32_16x16x32_bf16 v[66:69], v[154:157], v[166:169], v[66:69]
	v_mfma_f32_16x16x32_bf16 v[62:65], v[146:149], v[178:181], v[62:65]
	v_mfma_f32_16x16x32_bf16 v[58:61], v[154:157], v[178:181], v[58:61]
	v_mfma_f32_16x16x32_bf16 v[54:57], v[146:149], v[182:185], v[54:57]
	v_mfma_f32_16x16x32_bf16 v[50:53], v[154:157], v[182:185], v[50:53]
	v_mfma_f32_16x16x32_bf16 v[82:85], v[150:153], v[170:173], v[82:85]
	v_mfma_f32_16x16x32_bf16 v[74:77], v[158:161], v[170:173], v[74:77]
	v_mfma_f32_16x16x32_bf16 v[70:73], v[150:153], v[174:177], v[70:73]
	v_mfma_f32_16x16x32_bf16 v[66:69], v[158:161], v[174:177], v[66:69]
	v_mfma_f32_16x16x32_bf16 v[62:65], v[150:153], v[186:189], v[62:65]
	v_mfma_f32_16x16x32_bf16 v[58:61], v[158:161], v[186:189], v[58:61]
	v_mfma_f32_16x16x32_bf16 v[54:57], v[150:153], v[190:193], v[54:57]
	v_mfma_f32_16x16x32_bf16 v[50:53], v[158:161], v[190:193], v[50:53]
	s_setprio 0
	s_barrier
	s_mov_b32 m0, s29
	s_add_i32 s61, s60, 0x80
	ds_read_b128 v[162:165], v221 offset:49152
	ds_read_b128 v[166:169], v221 offset:51200
	ds_read_b128 v[170:173], v222 offset:49152
	ds_read_b128 v[174:177], v222 offset:51200
	ds_read_b128 v[178:181], v221 offset:53248
	ds_read_b128 v[182:185], v221 offset:55296
	ds_read_b128 v[186:189], v222 offset:53248
	ds_read_b128 v[190:193], v222 offset:55296
	buffer_load_dwordx4 v208, s[4:7], s61 offen lds
	s_mov_b32 m0, s30
	s_add_i32 s60, s60, 0x40080
	buffer_load_dwordx4 v210, s[4:7], s61 offen lds
	s_mov_b32 m0, s35
	s_nop 0
	buffer_load_dwordx4 v208, s[4:7], s60 offen lds
	s_mov_b32 m0, s36
	s_nop 0
	buffer_load_dwordx4 v210, s[4:7], s60 offen lds
	s_mov_b32 m0, s31
	s_nop 0
	buffer_load_dwordx4 v207, s[4:7], s59 offen lds
	s_mov_b32 m0, s34
	s_nop 0
	buffer_load_dwordx4 v209, s[4:7], s59 offen lds
	s_waitcnt vmcnt(8)
	s_waitcnt lgkmcnt(0)
	s_barrier
	s_setprio 1
	s_waitcnt lgkmcnt(7)
	v_mfma_f32_16x16x32_bf16 v[78:81], v[130:133], v[162:165], v[78:81]
	v_mfma_f32_16x16x32_bf16 v[46:49], v[138:141], v[162:165], v[46:49]
	s_waitcnt lgkmcnt(6)
	v_mfma_f32_16x16x32_bf16 v[42:45], v[130:133], v[166:169], v[42:45]
	v_mfma_f32_16x16x32_bf16 v[38:41], v[138:141], v[166:169], v[38:41]
	s_waitcnt lgkmcnt(3)
	v_mfma_f32_16x16x32_bf16 v[34:37], v[130:133], v[178:181], v[34:37]
	v_mfma_f32_16x16x32_bf16 v[30:33], v[138:141], v[178:181], v[30:33]
	s_waitcnt lgkmcnt(2)
	v_mfma_f32_16x16x32_bf16 v[26:29], v[130:133], v[182:185], v[26:29]
	v_mfma_f32_16x16x32_bf16 v[22:25], v[138:141], v[182:185], v[22:25]
	v_mfma_f32_16x16x32_bf16 v[78:81], v[134:137], v[170:173], v[78:81]
	v_mfma_f32_16x16x32_bf16 v[46:49], v[142:145], v[170:173], v[46:49]
	v_mfma_f32_16x16x32_bf16 v[42:45], v[134:137], v[174:177], v[42:45]
	v_mfma_f32_16x16x32_bf16 v[38:41], v[142:145], v[174:177], v[38:41]
	s_waitcnt lgkmcnt(1)
	v_mfma_f32_16x16x32_bf16 v[34:37], v[134:137], v[186:189], v[34:37]
	v_mfma_f32_16x16x32_bf16 v[30:33], v[142:145], v[186:189], v[30:33]
	s_waitcnt lgkmcnt(0)
	v_mfma_f32_16x16x32_bf16 v[26:29], v[134:137], v[190:193], v[26:29]
	v_mfma_f32_16x16x32_bf16 v[22:25], v[142:145], v[190:193], v[22:25]
	s_setprio 0
	s_setprio 1
	v_mfma_f32_16x16x32_bf16 v[18:21], v[146:149], v[162:165], v[18:21]
	v_mfma_f32_16x16x32_bf16 v[14:17], v[154:157], v[162:165], v[14:17]
	v_mfma_f32_16x16x32_bf16 v[10:13], v[146:149], v[166:169], v[10:13]
	v_mfma_f32_16x16x32_bf16 v[6:9], v[154:157], v[166:169], v[6:9]
	v_mfma_f32_16x16x32_bf16 v[2:5], v[146:149], v[178:181], v[2:5]
	v_mfma_f32_16x16x32_bf16 v[126:129], v[154:157], v[178:181], v[126:129]
	v_mfma_f32_16x16x32_bf16 v[122:125], v[146:149], v[182:185], v[122:125]
	v_mfma_f32_16x16x32_bf16 v[118:121], v[154:157], v[182:185], v[118:121]
	v_mfma_f32_16x16x32_bf16 v[18:21], v[150:153], v[170:173], v[18:21]
	v_mfma_f32_16x16x32_bf16 v[14:17], v[158:161], v[170:173], v[14:17]
	v_mfma_f32_16x16x32_bf16 v[10:13], v[150:153], v[174:177], v[10:13]
	v_mfma_f32_16x16x32_bf16 v[6:9], v[158:161], v[174:177], v[6:9]
	v_mfma_f32_16x16x32_bf16 v[2:5], v[150:153], v[186:189], v[2:5]
	v_mfma_f32_16x16x32_bf16 v[126:129], v[158:161], v[186:189], v[126:129]
	v_mfma_f32_16x16x32_bf16 v[122:125], v[150:153], v[190:193], v[122:125]
	v_mfma_f32_16x16x32_bf16 v[118:121], v[158:161], v[190:193], v[118:121]
	s_setprio 0
	s_add_i32 s58, s58, 2
	s_addk_i32 s33, 0x100
	s_addk_i32 s57, 0x100
	s_cmp_gt_u32 s58, 13
	s_cbranch_scc0 my_rot_233
	s_barrier
	s_and_b64 vcc, exec, s[16:17]
	s_cbranch_vccz .LBB0_236
	s_barrier

.LBB0_545:
	s_lshl_b32 s4, s50, 19
	s_lshr_b32 s63, 16, s59
	s_lshr_b32 s54, s4, s33
	s_cmp_eq_u32 s33, 0
	s_cselect_b64 s[22:23], -1, 0
	s_and_b64 s[64:65], s[22:23], exec
	s_mov_b32 s4, 0x3a000000
	s_cselect_b32 s4, 0x12000000, s4
	s_mov_b32 s56, 0x1400000
	s_cselect_b32 s56, 0x1600000, s56
	s_add_i32 s54, s54, s4
	s_and_b64 s[64:65], s[2:3], exec
	s_cselect_b32 s64, s54, s55
	s_lshl_b32 s4, s52, 19
	s_lshr_b32 s55, s4, s33
	s_add_i32 s55, s55, s56
	s_and_b64 s[78:79], s[2:3], exec
	s_cselect_b32 s65, s55, s61
	s_lshr_b32 s56, 0x40000, s33
	s_addk_i32 s61, 0x200
	s_mov_b32 s78, 4
	s_branch .LBB0_546
my_rot_546:
	s_barrier
.LBB0_546:
	ds_read_b128 v[130:133], v211
	ds_read_b128 v[134:137], v212
	ds_read_b128 v[138:141], v213
	ds_read_b128 v[142:145], v214
	ds_read_b128 v[146:149], v215
	ds_read_b128 v[150:153], v216
	ds_read_b128 v[154:157], v217
	ds_read_b128 v[158:161], v218
	s_add_i32 s4, s62, 0x80
	s_cmp_eq_u32 s63, s78
	s_cselect_b32 s84, s64, s4
	s_cselect_b32 s82, s33, s59
	s_cselect_b32 s81, s65, s61
	s_cselect_b32 s80, s56, s60
	s_add_i32 s79, s84, 0x80
	s_add_i32 s83, s60, s62
	s_mov_b32 s4, s70
	s_mov_b32 m0, s43
	ds_read_b128 v[162:165], v219
	ds_read_b128 v[166:169], v219 offset:2048
	ds_read_b128 v[170:173], v220
	ds_read_b128 v[174:177], v220 offset:2048
	ds_read_b128 v[178:181], v219 offset:4096
	ds_read_b128 v[182:185], v219 offset:6144
	ds_read_b128 v[186:189], v220 offset:4096
	ds_read_b128 v[190:193], v220 offset:6144
	buffer_load_dwordx4 v194, s[4:7], s83 offen lds
	s_mov_b32 m0, s44
	s_nop 0
	buffer_load_dwordx4 v222, s[4:7], s83 offen lds
	s_waitcnt vmcnt(8)
	s_waitcnt lgkmcnt(0)
	s_barrier
	s_setprio 1
	s_waitcnt lgkmcnt(7)
	v_mfma_f32_16x16x32_bf16 v[126:129], v[130:133], v[162:165], v[126:129]
	v_mfma_f32_16x16x32_bf16 v[122:125], v[138:141], v[162:165], v[122:125]
	s_waitcnt lgkmcnt(6)
	v_mfma_f32_16x16x32_bf16 v[118:121], v[130:133], v[166:169], v[118:121]
	v_mfma_f32_16x16x32_bf16 v[114:117], v[138:141], v[166:169], v[114:117]
	s_waitcnt lgkmcnt(3)
	v_mfma_f32_16x16x32_bf16 v[110:113], v[130:133], v[178:181], v[110:113]
	v_mfma_f32_16x16x32_bf16 v[106:109], v[138:141], v[178:181], v[106:109]
	s_waitcnt lgkmcnt(2)
	v_mfma_f32_16x16x32_bf16 v[102:105], v[130:133], v[182:185], v[102:105]
	v_mfma_f32_16x16x32_bf16 v[98:101], v[138:141], v[182:185], v[98:101]
	v_mfma_f32_16x16x32_bf16 v[126:129], v[134:137], v[170:173], v[126:129]
	v_mfma_f32_16x16x32_bf16 v[122:125], v[142:145], v[170:173], v[122:125]
	v_mfma_f32_16x16x32_bf16 v[118:121], v[134:137], v[174:177], v[118:121]
	v_mfma_f32_16x16x32_bf16 v[114:117], v[142:145], v[174:177], v[114:117]
	s_waitcnt lgkmcnt(1)
	v_mfma_f32_16x16x32_bf16 v[110:113], v[134:137], v[186:189], v[110:113]
	v_mfma_f32_16x16x32_bf16 v[106:109], v[142:145], v[186:189], v[106:109]
	s_waitcnt lgkmcnt(0)
	v_mfma_f32_16x16x32_bf16 v[102:105], v[134:137], v[190:193], v[102:105]
	v_mfma_f32_16x16x32_bf16 v[98:101], v[142:145], v[190:193], v[98:101]
	s_setprio 0
	s_setprio 1
	v_mfma_f32_16x16x32_bf16 v[94:97], v[146:149], v[162:165], v[94:97]
	v_mfma_f32_16x16x32_bf16 v[90:93], v[154:157], v[162:165], v[90:93]
	v_mfma_f32_16x16x32_bf16 v[86:89], v[146:149], v[166:169], v[86:89]
	v_mfma_f32_16x16x32_bf16 v[82:85], v[154:157], v[166:169], v[82:85]
	v_mfma_f32_16x16x32_bf16 v[78:81], v[146:149], v[178:181], v[78:81]
	v_mfma_f32_16x16x32_bf16 v[74:77], v[154:157], v[178:181], v[74:77]
	v_mfma_f32_16x16x32_bf16 v[70:73], v[146:149], v[182:185], v[70:73]
	v_mfma_f32_16x16x32_bf16 v[66:69], v[154:157], v[182:185], v[66:69]
	v_mfma_f32_16x16x32_bf16 v[94:97], v[150:153], v[170:173], v[94:97]
	v_mfma_f32_16x16x32_bf16 v[90:93], v[158:161], v[170:173], v[90:93]
	v_mfma_f32_16x16x32_bf16 v[86:89], v[150:153], v[174:177], v[86:89]
	v_mfma_f32_16x16x32_bf16 v[82:85], v[158:161], v[174:177], v[82:85]
	v_mfma_f32_16x16x32_bf16 v[78:81], v[150:153], v[186:189], v[78:81]
	v_mfma_f32_16x16x32_bf16 v[74:77], v[158:161], v[186:189], v[74:77]
	v_mfma_f32_16x16x32_bf16 v[70:73], v[150:153], v[190:193], v[70:73]
	v_mfma_f32_16x16x32_bf16 v[66:69], v[158:161], v[190:193], v[66:69]
	s_setprio 0
	s_barrier
	s_cmp_eq_u32 s82, 0
	s_cselect_b64 s[82:83], -1, 0
	v_cndmask_b32_e64 v233, v200, 0, s[82:83]
	s_mov_b32 m0, s25
	v_sub_u32_e32 v233, v201, v233
	v_cndmask_b32_e64 v234, v203, 0, s[82:83]
	ds_read_b128 v[162:165], v219 offset:16384
	ds_read_b128 v[166:169], v219 offset:18432
	ds_read_b128 v[170:173], v220 offset:16384
	ds_read_b128 v[174:177], v220 offset:18432
	ds_read_b128 v[178:181], v219 offset:20480
	ds_read_b128 v[182:185], v219 offset:22528
	ds_read_b128 v[186:189], v220 offset:20480
	ds_read_b128 v[190:193], v220 offset:22528
	buffer_load_dwordx4 v233, s[4:7], s81 offen lds
	v_sub_u32_e32 v234, v204, v234
	s_mov_b32 m0, s26
	s_add_i32 s85, s81, s80
	buffer_load_dwordx4 v234, s[4:7], s81 offen lds
	s_mov_b32 m0, s27
	v_cndmask_b32_e64 v235, v205, 0, s[82:83]
	buffer_load_dwordx4 v233, s[4:7], s85 offen lds
	s_mov_b32 m0, s28
	v_sub_u32_e32 v235, v1, v235
	buffer_load_dwordx4 v234, s[4:7], s85 offen lds
	s_mov_b32 m0, s24
	v_cndmask_b32_e64 v236, v206, 0, s[82:83]
	buffer_load_dwordx4 v235, s[4:7], s84 offen lds
	v_sub_u32_e32 v236, v202, v236
	s_mov_b32 m0, s29
	s_nop 0
	buffer_load_dwordx4 v236, s[4:7], s84 offen lds
	s_waitcnt vmcnt(8)
	s_waitcnt lgkmcnt(0)
	s_barrier
	s_setprio 1
	s_waitcnt lgkmcnt(7)
	v_mfma_f32_16x16x32_bf16 v[62:65], v[130:133], v[162:165], v[62:65]
	v_mfma_f32_16x16x32_bf16 v[58:61], v[138:141], v[162:165], v[58:61]
	s_waitcnt lgkmcnt(6)
	v_mfma_f32_16x16x32_bf16 v[54:57], v[130:133], v[166:169], v[54:57]
	v_mfma_f32_16x16x32_bf16 v[50:53], v[138:141], v[166:169], v[50:53]
	s_waitcnt lgkmcnt(3)
	v_mfma_f32_16x16x32_bf16 v[46:49], v[130:133], v[178:181], v[46:49]
	v_mfma_f32_16x16x32_bf16 v[42:45], v[138:141], v[178:181], v[42:45]
	s_waitcnt lgkmcnt(2)
	v_mfma_f32_16x16x32_bf16 v[38:41], v[130:133], v[182:185], v[38:41]
	v_mfma_f32_16x16x32_bf16 v[34:37], v[138:141], v[182:185], v[34:37]
	v_mfma_f32_16x16x32_bf16 v[62:65], v[134:137], v[170:173], v[62:65]
	v_mfma_f32_16x16x32_bf16 v[58:61], v[142:145], v[170:173], v[58:61]
	v_mfma_f32_16x16x32_bf16 v[54:57], v[134:137], v[174:177], v[54:57]
	v_mfma_f32_16x16x32_bf16 v[50:53], v[142:145], v[174:177], v[50:53]
	s_waitcnt lgkmcnt(1)
	v_mfma_f32_16x16x32_bf16 v[46:49], v[134:137], v[186:189], v[46:49]
	v_mfma_f32_16x16x32_bf16 v[42:45], v[142:145], v[186:189], v[42:45]
	s_waitcnt lgkmcnt(0)
	v_mfma_f32_16x16x32_bf16 v[38:41], v[134:137], v[190:193], v[38:41]
	v_mfma_f32_16x16x32_bf16 v[34:37], v[142:145], v[190:193], v[34:37]
	s_setprio 0
	s_setprio 1
	v_mfma_f32_16x16x32_bf16 v[30:33], v[146:149], v[162:165], v[30:33]
	v_mfma_f32_16x16x32_bf16 v[26:29], v[154:157], v[162:165], v[26:29]
	v_mfma_f32_16x16x32_bf16 v[22:25], v[146:149], v[166:169], v[22:25]
	v_mfma_f32_16x16x32_bf16 v[18:21], v[154:157], v[166:169], v[18:21]
	v_mfma_f32_16x16x32_bf16 v[14:17], v[146:149], v[178:181], v[14:17]
	v_mfma_f32_16x16x32_bf16 v[10:13], v[154:157], v[178:181], v[10:13]
	v_mfma_f32_16x16x32_bf16 v[6:9], v[146:149], v[182:185], v[6:9]
	v_mfma_f32_16x16x32_bf16 v[2:5], v[154:157], v[182:185], v[2:5]
	v_mfma_f32_16x16x32_bf16 v[30:33], v[150:153], v[170:173], v[30:33]
	v_mfma_f32_16x16x32_bf16 v[26:29], v[158:161], v[170:173], v[26:29]
	v_mfma_f32_16x16x32_bf16 v[22:25], v[150:153], v[174:177], v[22:25]
	v_mfma_f32_16x16x32_bf16 v[18:21], v[158:161], v[174:177], v[18:21]
	v_mfma_f32_16x16x32_bf16 v[14:17], v[150:153], v[186:189], v[14:17]
	v_mfma_f32_16x16x32_bf16 v[10:13], v[158:161], v[186:189], v[10:13]
	v_mfma_f32_16x16x32_bf16 v[6:9], v[150:153], v[190:193], v[6:9]
	v_mfma_f32_16x16x32_bf16 v[2:5], v[158:161], v[190:193], v[2:5]
	s_setprio 0
	s_barrier
	ds_read_b128 v[130:133], v223
	ds_read_b128 v[134:137], v224
	ds_read_b128 v[138:141], v225
	ds_read_b128 v[142:145], v227
	ds_read_b128 v[146:149], v228
	ds_read_b128 v[150:153], v229
	ds_read_b128 v[154:157], v230
	ds_read_b128 v[158:161], v231
	s_add_i32 s84, s84, s80
	s_mov_b32 m0, s30
	ds_read_b128 v[162:165], v219 offset:32768
	ds_read_b128 v[166:169], v219 offset:34816
	ds_read_b128 v[170:173], v220 offset:32768
	ds_read_b128 v[174:177], v220 offset:34816
	ds_read_b128 v[178:181], v219 offset:36864
	ds_read_b128 v[182:185], v219 offset:38912
	ds_read_b128 v[186:189], v220 offset:36864
	ds_read_b128 v[190:193], v220 offset:38912
	buffer_load_dwordx4 v235, s[4:7], s84 offen lds
	s_mov_b32 m0, s31
	s_nop 0
	buffer_load_dwordx4 v236, s[4:7], s84 offen lds
	s_waitcnt vmcnt(8)
	s_waitcnt lgkmcnt(0)
	s_barrier
	s_setprio 1
	s_waitcnt lgkmcnt(7)
	v_mfma_f32_16x16x32_bf16 v[126:129], v[130:133], v[162:165], v[126:129]
	v_mfma_f32_16x16x32_bf16 v[122:125], v[138:141], v[162:165], v[122:125]
	s_waitcnt lgkmcnt(6)
	v_mfma_f32_16x16x32_bf16 v[118:121], v[130:133], v[166:169], v[118:121]
	v_mfma_f32_16x16x32_bf16 v[114:117], v[138:141], v[166:169], v[114:117]
	s_waitcnt lgkmcnt(3)
	v_mfma_f32_16x16x32_bf16 v[110:113], v[130:133], v[178:181], v[110:113]
	v_mfma_f32_16x16x32_bf16 v[106:109], v[138:141], v[178:181], v[106:109]
	s_waitcnt lgkmcnt(2)
	v_mfma_f32_16x16x32_bf16 v[102:105], v[130:133], v[182:185], v[102:105]
	v_mfma_f32_16x16x32_bf16 v[98:101], v[138:141], v[182:185], v[98:101]
	v_mfma_f32_16x16x32_bf16 v[126:129], v[134:137], v[170:173], v[126:129]
	v_mfma_f32_16x16x32_bf16 v[122:125], v[142:145], v[170:173], v[122:125]
	v_mfma_f32_16x16x32_bf16 v[118:121], v[134:137], v[174:177], v[118:121]
	v_mfma_f32_16x16x32_bf16 v[114:117], v[142:145], v[174:177], v[114:117]
	s_waitcnt lgkmcnt(1)
	v_mfma_f32_16x16x32_bf16 v[110:113], v[134:137], v[186:189], v[110:113]
	v_mfma_f32_16x16x32_bf16 v[106:109], v[142:145], v[186:189], v[106:109]
	s_waitcnt lgkmcnt(0)
	v_mfma_f32_16x16x32_bf16 v[102:105], v[134:137], v[190:193], v[102:105]
	v_mfma_f32_16x16x32_bf16 v[98:101], v[142:145], v[190:193], v[98:101]
	s_setprio 0
	s_setprio 1
	v_mfma_f32_16x16x32_bf16 v[94:97], v[146:149], v[162:165], v[94:97]
	v_mfma_f32_16x16x32_bf16 v[90:93], v[154:157], v[162:165], v[90:93]
	v_mfma_f32_16x16x32_bf16 v[86:89], v[146:149], v[166:169], v[86:89]
	v_mfma_f32_16x16x32_bf16 v[82:85], v[154:157], v[166:169], v[82:85]
	v_mfma_f32_16x16x32_bf16 v[78:81], v[146:149], v[178:181], v[78:81]
	v_mfma_f32_16x16x32_bf16 v[74:77], v[154:157], v[178:181], v[74:77]
	v_mfma_f32_16x16x32_bf16 v[70:73], v[146:149], v[182:185], v[70:73]
	v_mfma_f32_16x16x32_bf16 v[66:69], v[154:157], v[182:185], v[66:69]
	v_mfma_f32_16x16x32_bf16 v[94:97], v[150:153], v[170:173], v[94:97]
	v_mfma_f32_16x16x32_bf16 v[90:93], v[158:161], v[170:173], v[90:93]
	v_mfma_f32_16x16x32_bf16 v[86:89], v[150:153], v[174:177], v[86:89]
	v_mfma_f32_16x16x32_bf16 v[82:85], v[158:161], v[174:177], v[82:85]
	v_mfma_f32_16x16x32_bf16 v[78:81], v[150:153], v[186:189], v[78:81]
	v_mfma_f32_16x16x32_bf16 v[74:77], v[158:161], v[186:189], v[74:77]
	v_mfma_f32_16x16x32_bf16 v[70:73], v[150:153], v[190:193], v[70:73]
	v_mfma_f32_16x16x32_bf16 v[66:69], v[158:161], v[190:193], v[66:69]
	s_setprio 0
	s_barrier
	s_mov_b32 m0, s36
	s_addk_i32 s81, 0x80
	ds_read_b128 v[162:165], v219 offset:49152
	ds_read_b128 v[166:169], v219 offset:51200
	ds_read_b128 v[170:173], v220 offset:49152
	ds_read_b128 v[174:177], v220 offset:51200
	ds_read_b128 v[178:181], v219 offset:53248
	ds_read_b128 v[182:185], v219 offset:55296
	ds_read_b128 v[186:189], v220 offset:53248
	ds_read_b128 v[190:193], v220 offset:55296
	buffer_load_dwordx4 v233, s[4:7], s81 offen lds
	s_mov_b32 m0, s37
	s_nop 0
	buffer_load_dwordx4 v234, s[4:7], s81 offen lds
	s_add_i32 s81, s81, s80
	s_mov_b32 m0, s40
	s_nop 0
	buffer_load_dwordx4 v233, s[4:7], s81 offen lds
	s_mov_b32 m0, s41
	s_nop 0
	buffer_load_dwordx4 v234, s[4:7], s81 offen lds
	s_mov_b32 m0, s38
	s_nop 0
	buffer_load_dwordx4 v235, s[4:7], s79 offen lds
	s_mov_b32 m0, s39
	s_nop 0
	buffer_load_dwordx4 v236, s[4:7], s79 offen lds
	s_waitcnt vmcnt(8)
	s_waitcnt lgkmcnt(0)
	s_barrier
	s_setprio 1
	s_waitcnt lgkmcnt(7)
	v_mfma_f32_16x16x32_bf16 v[62:65], v[130:133], v[162:165], v[62:65]
	v_mfma_f32_16x16x32_bf16 v[58:61], v[138:141], v[162:165], v[58:61]
	s_waitcnt lgkmcnt(6)
	v_mfma_f32_16x16x32_bf16 v[54:57], v[130:133], v[166:169], v[54:57]
	v_mfma_f32_16x16x32_bf16 v[50:53], v[138:141], v[166:169], v[50:53]
	s_waitcnt lgkmcnt(3)
	v_mfma_f32_16x16x32_bf16 v[46:49], v[130:133], v[178:181], v[46:49]
	v_mfma_f32_16x16x32_bf16 v[42:45], v[138:141], v[178:181], v[42:45]
	s_waitcnt lgkmcnt(2)
	v_mfma_f32_16x16x32_bf16 v[38:41], v[130:133], v[182:185], v[38:41]
	v_mfma_f32_16x16x32_bf16 v[34:37], v[138:141], v[182:185], v[34:37]
	v_mfma_f32_16x16x32_bf16 v[62:65], v[134:137], v[170:173], v[62:65]
	v_mfma_f32_16x16x32_bf16 v[58:61], v[142:145], v[170:173], v[58:61]
	v_mfma_f32_16x16x32_bf16 v[54:57], v[134:137], v[174:177], v[54:57]
	v_mfma_f32_16x16x32_bf16 v[50:53], v[142:145], v[174:177], v[50:53]
	s_waitcnt lgkmcnt(1)
	v_mfma_f32_16x16x32_bf16 v[46:49], v[134:137], v[186:189], v[46:49]
	v_mfma_f32_16x16x32_bf16 v[42:45], v[142:145], v[186:189], v[42:45]
	s_waitcnt lgkmcnt(0)
	v_mfma_f32_16x16x32_bf16 v[38:41], v[134:137], v[190:193], v[38:41]
	v_mfma_f32_16x16x32_bf16 v[34:37], v[142:145], v[190:193], v[34:37]
	s_setprio 0
	s_setprio 1
	v_mfma_f32_16x16x32_bf16 v[30:33], v[146:149], v[162:165], v[30:33]
	v_mfma_f32_16x16x32_bf16 v[26:29], v[154:157], v[162:165], v[26:29]
	v_mfma_f32_16x16x32_bf16 v[22:25], v[146:149], v[166:169], v[22:25]
	v_mfma_f32_16x16x32_bf16 v[18:21], v[154:157], v[166:169], v[18:21]
	v_mfma_f32_16x16x32_bf16 v[14:17], v[146:149], v[178:181], v[14:17]
	v_mfma_f32_16x16x32_bf16 v[10:13], v[154:157], v[178:181], v[10:13]
	v_mfma_f32_16x16x32_bf16 v[6:9], v[146:149], v[182:185], v[6:9]
	v_mfma_f32_16x16x32_bf16 v[2:5], v[154:157], v[182:185], v[2:5]
	v_mfma_f32_16x16x32_bf16 v[30:33], v[150:153], v[170:173], v[30:33]
	v_mfma_f32_16x16x32_bf16 v[26:29], v[158:161], v[170:173], v[26:29]
	v_mfma_f32_16x16x32_bf16 v[22:25], v[150:153], v[174:177], v[22:25]
	v_mfma_f32_16x16x32_bf16 v[18:21], v[158:161], v[174:177], v[18:21]
	v_mfma_f32_16x16x32_bf16 v[14:17], v[150:153], v[186:189], v[14:17]
	v_mfma_f32_16x16x32_bf16 v[10:13], v[158:161], v[186:189], v[10:13]
	v_mfma_f32_16x16x32_bf16 v[6:9], v[150:153], v[190:193], v[6:9]
	v_mfma_f32_16x16x32_bf16 v[2:5], v[158:161], v[190:193], v[2:5]
	s_setprio 0
	s_add_i32 s4, s78, 2
	s_addk_i32 s62, 0x100
	s_addk_i32 s61, 0x100
	s_cmp_ge_u32 s78, s63
	s_mov_b32 s78, s4
	s_cbranch_scc0 my_rot_546
	s_barrier
	s_and_b64 vcc, exec, s[12:13]
	s_cbranch_vccz .LBB0_549
	s_barrier

.LBB0_840:
	s_lshl_b32 s63, s61, 19
	v_cmp_lt_i64_e32 vcc, s[0:1], v[228:229]
	s_add_i32 s63, s63, 0x32000000
	s_and_b64 s[0:1], vcc, exec
	s_cselect_b32 s0, s63, s42
	s_lshl_b32 s64, s60, 19
	s_add_i32 s64, s64, 0x1800000
	s_and_b64 s[4:5], vcc, exec
	s_cselect_b32 s1, s64, s34
	s_mov_b32 s4, 0
	s_movk_i32 s5, 0xfa00
	s_branch .LBB0_841
my_rot_841:
	s_barrier
.LBB0_841:
	ds_read_b128 v[130:133], v240
	ds_read_b128 v[134:137], v241
	ds_read_b128 v[138:141], v242
	ds_read_b128 v[142:145], v243
	ds_read_b128 v[146:149], v244
	ds_read_b128 v[150:153], v245
	ds_read_b128 v[154:157], v246
	ds_read_b128 v[158:161], v247
	s_add_i32 s8, s42, s5
	s_add_i32 s19, s34, s5
	s_add_i32 s18, s8, 0x800
	s_addk_i32 s19, 0x800
	s_cmp_eq_u32 s5, 0
	s_cselect_b32 s20, s0, s18
	s_cselect_b32 s19, s1, s19
	s_add_i32 s18, s20, 0x80
	s_add_i32 s21, s8, 0x40780
	s_mov_b32 s8, s70
	s_mov_b32 m0, s52
	ds_read_b128 v[162:165], v248
	ds_read_b128 v[166:169], v248 offset:2048
	ds_read_b128 v[170:173], v249
	ds_read_b128 v[174:177], v249 offset:2048
	ds_read_b128 v[178:181], v248 offset:4096
	ds_read_b128 v[182:185], v248 offset:6144
	ds_read_b128 v[186:189], v249 offset:4096
	ds_read_b128 v[190:193], v249 offset:6144
	buffer_load_dwordx4 v1, s[8:11], s21 offen lds
	s_mov_b32 m0, s53
	s_nop 0
	buffer_load_dwordx4 v234, s[8:11], s21 offen lds
	s_waitcnt vmcnt(8)
	s_waitcnt lgkmcnt(0)
	s_barrier
	s_setprio 1
	s_waitcnt lgkmcnt(7)
	v_mfma_f32_16x16x32_bf16 v[74:77], v[130:133], v[162:165], v[74:77]
	v_mfma_f32_16x16x32_bf16 v[70:73], v[138:141], v[162:165], v[70:73]
	s_waitcnt lgkmcnt(6)
	v_mfma_f32_16x16x32_bf16 v[66:69], v[130:133], v[166:169], v[66:69]
	v_mfma_f32_16x16x32_bf16 v[82:85], v[138:141], v[166:169], v[82:85]
	s_waitcnt lgkmcnt(3)
	v_mfma_f32_16x16x32_bf16 v[78:81], v[130:133], v[178:181], v[78:81]
	v_mfma_f32_16x16x32_bf16 v[90:93], v[138:141], v[178:181], v[90:93]
	s_waitcnt lgkmcnt(2)
	v_mfma_f32_16x16x32_bf16 v[86:89], v[130:133], v[182:185], v[86:89]
	v_mfma_f32_16x16x32_bf16 v[102:105], v[138:141], v[182:185], v[102:105]
	v_mfma_f32_16x16x32_bf16 v[74:77], v[134:137], v[170:173], v[74:77]
	v_mfma_f32_16x16x32_bf16 v[70:73], v[142:145], v[170:173], v[70:73]
	v_mfma_f32_16x16x32_bf16 v[66:69], v[134:137], v[174:177], v[66:69]
	v_mfma_f32_16x16x32_bf16 v[82:85], v[142:145], v[174:177], v[82:85]
	s_waitcnt lgkmcnt(1)
	v_mfma_f32_16x16x32_bf16 v[78:81], v[134:137], v[186:189], v[78:81]
	v_mfma_f32_16x16x32_bf16 v[90:93], v[142:145], v[186:189], v[90:93]
	s_waitcnt lgkmcnt(0)
	v_mfma_f32_16x16x32_bf16 v[86:89], v[134:137], v[190:193], v[86:89]
	v_mfma_f32_16x16x32_bf16 v[102:105], v[142:145], v[190:193], v[102:105]
	s_setprio 0
	s_setprio 1
	v_mfma_f32_16x16x32_bf16 v[98:101], v[146:149], v[162:165], v[98:101]
	v_mfma_f32_16x16x32_bf16 v[94:97], v[154:157], v[162:165], v[94:97]
	v_mfma_f32_16x16x32_bf16 v[106:109], v[146:149], v[166:169], v[106:109]
	v_mfma_f32_16x16x32_bf16 v[110:113], v[154:157], v[166:169], v[110:113]
	v_mfma_f32_16x16x32_bf16 v[114:117], v[146:149], v[178:181], v[114:117]
	v_mfma_f32_16x16x32_bf16 v[118:121], v[154:157], v[178:181], v[118:121]
	v_mfma_f32_16x16x32_bf16 v[122:125], v[146:149], v[182:185], v[122:125]
	v_mfma_f32_16x16x32_bf16 v[126:129], v[154:157], v[182:185], v[126:129]
	v_mfma_f32_16x16x32_bf16 v[98:101], v[150:153], v[170:173], v[98:101]
	v_mfma_f32_16x16x32_bf16 v[94:97], v[158:161], v[170:173], v[94:97]
	v_mfma_f32_16x16x32_bf16 v[106:109], v[150:153], v[174:177], v[106:109]
	v_mfma_f32_16x16x32_bf16 v[110:113], v[158:161], v[174:177], v[110:113]
	v_mfma_f32_16x16x32_bf16 v[114:117], v[150:153], v[186:189], v[114:117]
	v_mfma_f32_16x16x32_bf16 v[118:121], v[158:161], v[186:189], v[118:121]
	v_mfma_f32_16x16x32_bf16 v[122:125], v[150:153], v[190:193], v[122:125]
	v_mfma_f32_16x16x32_bf16 v[126:129], v[158:161], v[190:193], v[126:129]
	s_setprio 0
	s_barrier
	s_mov_b32 m0, s29
	ds_read_b128 v[162:165], v248 offset:16384
	ds_read_b128 v[166:169], v248 offset:18432
	ds_read_b128 v[170:173], v249 offset:16384
	ds_read_b128 v[174:177], v249 offset:18432
	ds_read_b128 v[178:181], v248 offset:20480
	ds_read_b128 v[182:185], v248 offset:22528
	ds_read_b128 v[186:189], v249 offset:20480
	ds_read_b128 v[190:193], v249 offset:22528
	buffer_load_dwordx4 v233, s[8:11], s19 offen lds
	s_mov_b32 m0, s30
	s_add_i32 s21, s19, 0x40000
	buffer_load_dwordx4 v235, s[8:11], s19 offen lds
	s_mov_b32 m0, s31
	s_nop 0
	buffer_load_dwordx4 v233, s[8:11], s21 offen lds
	s_mov_b32 m0, s35
	s_nop 0
	buffer_load_dwordx4 v235, s[8:11], s21 offen lds
	s_mov_b32 m0, s28
	s_nop 0
	buffer_load_dwordx4 v1, s[8:11], s20 offen lds
	s_mov_b32 m0, s38
	s_nop 0
	buffer_load_dwordx4 v234, s[8:11], s20 offen lds
	s_waitcnt vmcnt(8)
	s_waitcnt lgkmcnt(0)
	s_barrier
	s_setprio 1
	s_waitcnt lgkmcnt(7)
	v_mfma_f32_16x16x32_bf16 v[10:13], v[130:133], v[162:165], v[10:13]
	v_mfma_f32_16x16x32_bf16 v[6:9], v[138:141], v[162:165], v[6:9]
	s_waitcnt lgkmcnt(6)
	v_mfma_f32_16x16x32_bf16 v[2:5], v[130:133], v[166:169], v[2:5]
	v_mfma_f32_16x16x32_bf16 v[18:21], v[138:141], v[166:169], v[18:21]
	s_waitcnt lgkmcnt(3)
	v_mfma_f32_16x16x32_bf16 v[14:17], v[130:133], v[178:181], v[14:17]
	v_mfma_f32_16x16x32_bf16 v[26:29], v[138:141], v[178:181], v[26:29]
	s_waitcnt lgkmcnt(2)
	v_mfma_f32_16x16x32_bf16 v[22:25], v[130:133], v[182:185], v[22:25]
	v_mfma_f32_16x16x32_bf16 v[38:41], v[138:141], v[182:185], v[38:41]
	v_mfma_f32_16x16x32_bf16 v[10:13], v[134:137], v[170:173], v[10:13]
	v_mfma_f32_16x16x32_bf16 v[6:9], v[142:145], v[170:173], v[6:9]
	v_mfma_f32_16x16x32_bf16 v[2:5], v[134:137], v[174:177], v[2:5]
	v_mfma_f32_16x16x32_bf16 v[18:21], v[142:145], v[174:177], v[18:21]
	s_waitcnt lgkmcnt(1)
	v_mfma_f32_16x16x32_bf16 v[14:17], v[134:137], v[186:189], v[14:17]
	v_mfma_f32_16x16x32_bf16 v[26:29], v[142:145], v[186:189], v[26:29]
	s_waitcnt lgkmcnt(0)
	v_mfma_f32_16x16x32_bf16 v[22:25], v[134:137], v[190:193], v[22:25]
	v_mfma_f32_16x16x32_bf16 v[38:41], v[142:145], v[190:193], v[38:41]
	s_setprio 0
	s_setprio 1
	v_mfma_f32_16x16x32_bf16 v[34:37], v[146:149], v[162:165], v[34:37]
	v_mfma_f32_16x16x32_bf16 v[30:33], v[154:157], v[162:165], v[30:33]
	v_mfma_f32_16x16x32_bf16 v[42:45], v[146:149], v[166:169], v[42:45]
	v_mfma_f32_16x16x32_bf16 v[46:49], v[154:157], v[166:169], v[46:49]
	v_mfma_f32_16x16x32_bf16 v[50:53], v[146:149], v[178:181], v[50:53]
	v_mfma_f32_16x16x32_bf16 v[54:57], v[154:157], v[178:181], v[54:57]
	v_mfma_f32_16x16x32_bf16 v[58:61], v[146:149], v[182:185], v[58:61]
	v_mfma_f32_16x16x32_bf16 v[62:65], v[154:157], v[182:185], v[62:65]
	v_mfma_f32_16x16x32_bf16 v[34:37], v[150:153], v[170:173], v[34:37]
	v_mfma_f32_16x16x32_bf16 v[30:33], v[158:161], v[170:173], v[30:33]
	v_mfma_f32_16x16x32_bf16 v[42:45], v[150:153], v[174:177], v[42:45]
	v_mfma_f32_16x16x32_bf16 v[46:49], v[158:161], v[174:177], v[46:49]
	v_mfma_f32_16x16x32_bf16 v[50:53], v[150:153], v[186:189], v[50:53]
	v_mfma_f32_16x16x32_bf16 v[54:57], v[158:161], v[186:189], v[54:57]
	v_mfma_f32_16x16x32_bf16 v[58:61], v[150:153], v[190:193], v[58:61]
	v_mfma_f32_16x16x32_bf16 v[62:65], v[158:161], v[190:193], v[62:65]
	s_setprio 0
	s_barrier
	ds_read_b128 v[130:133], v194
	ds_read_b128 v[134:137], v195
	ds_read_b128 v[138:141], v196
	ds_read_b128 v[142:145], v197
	ds_read_b128 v[146:149], v198
	ds_read_b128 v[150:153], v199
	ds_read_b128 v[154:157], v200
	ds_read_b128 v[158:161], v201
	s_add_i32 s20, s20, 0x40000
	s_mov_b32 m0, s39
	ds_read_b128 v[162:165], v248 offset:32768
	ds_read_b128 v[166:169], v248 offset:34816
	ds_read_b128 v[170:173], v249 offset:32768
	ds_read_b128 v[174:177], v249 offset:34816
	ds_read_b128 v[178:181], v248 offset:36864
	ds_read_b128 v[182:185], v248 offset:38912
	ds_read_b128 v[186:189], v249 offset:36864
	ds_read_b128 v[190:193], v249 offset:38912
	buffer_load_dwordx4 v1, s[8:11], s20 offen lds
	s_mov_b32 m0, s41
	s_nop 0
	buffer_load_dwordx4 v234, s[8:11], s20 offen lds
	s_waitcnt vmcnt(8)
	s_waitcnt lgkmcnt(0)
	s_barrier
	s_setprio 1
	s_waitcnt lgkmcnt(7)
	v_mfma_f32_16x16x32_bf16 v[74:77], v[130:133], v[162:165], v[74:77]
	v_mfma_f32_16x16x32_bf16 v[70:73], v[138:141], v[162:165], v[70:73]
	s_waitcnt lgkmcnt(6)
	v_mfma_f32_16x16x32_bf16 v[66:69], v[130:133], v[166:169], v[66:69]
	v_mfma_f32_16x16x32_bf16 v[82:85], v[138:141], v[166:169], v[82:85]
	s_waitcnt lgkmcnt(3)
	v_mfma_f32_16x16x32_bf16 v[78:81], v[130:133], v[178:181], v[78:81]
	v_mfma_f32_16x16x32_bf16 v[90:93], v[138:141], v[178:181], v[90:93]
	s_waitcnt lgkmcnt(2)
	v_mfma_f32_16x16x32_bf16 v[86:89], v[130:133], v[182:185], v[86:89]
	v_mfma_f32_16x16x32_bf16 v[102:105], v[138:141], v[182:185], v[102:105]
	v_mfma_f32_16x16x32_bf16 v[74:77], v[134:137], v[170:173], v[74:77]
	v_mfma_f32_16x16x32_bf16 v[70:73], v[142:145], v[170:173], v[70:73]
	v_mfma_f32_16x16x32_bf16 v[66:69], v[134:137], v[174:177], v[66:69]
	v_mfma_f32_16x16x32_bf16 v[82:85], v[142:145], v[174:177], v[82:85]
	s_waitcnt lgkmcnt(1)
	v_mfma_f32_16x16x32_bf16 v[78:81], v[134:137], v[186:189], v[78:81]
	v_mfma_f32_16x16x32_bf16 v[90:93], v[142:145], v[186:189], v[90:93]
	s_waitcnt lgkmcnt(0)
	v_mfma_f32_16x16x32_bf16 v[86:89], v[134:137], v[190:193], v[86:89]
	v_mfma_f32_16x16x32_bf16 v[102:105], v[142:145], v[190:193], v[102:105]
	s_setprio 0
	s_setprio 1
	v_mfma_f32_16x16x32_bf16 v[98:101], v[146:149], v[162:165], v[98:101]
	v_mfma_f32_16x16x32_bf16 v[94:97], v[154:157], v[162:165], v[94:97]
	v_mfma_f32_16x16x32_bf16 v[106:109], v[146:149], v[166:169], v[106:109]
	v_mfma_f32_16x16x32_bf16 v[110:113], v[154:157], v[166:169], v[110:113]
	v_mfma_f32_16x16x32_bf16 v[114:117], v[146:149], v[178:181], v[114:117]
	v_mfma_f32_16x16x32_bf16 v[118:121], v[154:157], v[178:181], v[118:121]
	v_mfma_f32_16x16x32_bf16 v[122:125], v[146:149], v[182:185], v[122:125]
	v_mfma_f32_16x16x32_bf16 v[126:129], v[154:157], v[182:185], v[126:129]
	v_mfma_f32_16x16x32_bf16 v[98:101], v[150:153], v[170:173], v[98:101]
	v_mfma_f32_16x16x32_bf16 v[94:97], v[158:161], v[170:173], v[94:97]
	v_mfma_f32_16x16x32_bf16 v[106:109], v[150:153], v[174:177], v[106:109]
	v_mfma_f32_16x16x32_bf16 v[110:113], v[158:161], v[174:177], v[110:113]
	v_mfma_f32_16x16x32_bf16 v[114:117], v[150:153], v[186:189], v[114:117]
	v_mfma_f32_16x16x32_bf16 v[118:121], v[158:161], v[186:189], v[118:121]
	v_mfma_f32_16x16x32_bf16 v[122:125], v[150:153], v[190:193], v[122:125]
	v_mfma_f32_16x16x32_bf16 v[126:129], v[158:161], v[190:193], v[126:129]
	s_setprio 0
	s_barrier
	s_mov_b32 m0, s44
	s_add_i32 s20, s19, 0x80
	ds_read_b128 v[162:165], v248 offset:49152
	ds_read_b128 v[166:169], v248 offset:51200
	ds_read_b128 v[170:173], v249 offset:49152
	ds_read_b128 v[174:177], v249 offset:51200
	ds_read_b128 v[178:181], v248 offset:53248
	ds_read_b128 v[182:185], v248 offset:55296
	ds_read_b128 v[186:189], v249 offset:53248
	ds_read_b128 v[190:193], v249 offset:55296
	buffer_load_dwordx4 v233, s[8:11], s20 offen lds
	s_mov_b32 m0, s45
	s_add_i32 s19, s19, 0x40080
	buffer_load_dwordx4 v235, s[8:11], s20 offen lds
	s_mov_b32 m0, s48
	s_nop 0
	buffer_load_dwordx4 v233, s[8:11], s19 offen lds
	s_mov_b32 m0, s49
	s_nop 0
	buffer_load_dwordx4 v235, s[8:11], s19 offen lds
	s_mov_b32 m0, s46
	s_nop 0
	buffer_load_dwordx4 v1, s[8:11], s18 offen lds
	s_mov_b32 m0, s47
	s_nop 0
	buffer_load_dwordx4 v234, s[8:11], s18 offen lds
	s_waitcnt vmcnt(8)
	s_waitcnt lgkmcnt(0)
	s_barrier
	s_setprio 1
	s_waitcnt lgkmcnt(7)
	v_mfma_f32_16x16x32_bf16 v[10:13], v[130:133], v[162:165], v[10:13]
	v_mfma_f32_16x16x32_bf16 v[6:9], v[138:141], v[162:165], v[6:9]
	s_waitcnt lgkmcnt(6)
	v_mfma_f32_16x16x32_bf16 v[2:5], v[130:133], v[166:169], v[2:5]
	v_mfma_f32_16x16x32_bf16 v[18:21], v[138:141], v[166:169], v[18:21]
	s_waitcnt lgkmcnt(3)
	v_mfma_f32_16x16x32_bf16 v[14:17], v[130:133], v[178:181], v[14:17]
	v_mfma_f32_16x16x32_bf16 v[26:29], v[138:141], v[178:181], v[26:29]
	s_waitcnt lgkmcnt(2)
	v_mfma_f32_16x16x32_bf16 v[22:25], v[130:133], v[182:185], v[22:25]
	v_mfma_f32_16x16x32_bf16 v[38:41], v[138:141], v[182:185], v[38:41]
	v_mfma_f32_16x16x32_bf16 v[10:13], v[134:137], v[170:173], v[10:13]
	v_mfma_f32_16x16x32_bf16 v[6:9], v[142:145], v[170:173], v[6:9]
	v_mfma_f32_16x16x32_bf16 v[2:5], v[134:137], v[174:177], v[2:5]
	v_mfma_f32_16x16x32_bf16 v[18:21], v[142:145], v[174:177], v[18:21]
	s_waitcnt lgkmcnt(1)
	v_mfma_f32_16x16x32_bf16 v[14:17], v[134:137], v[186:189], v[14:17]
	v_mfma_f32_16x16x32_bf16 v[26:29], v[142:145], v[186:189], v[26:29]
	s_waitcnt lgkmcnt(0)
	v_mfma_f32_16x16x32_bf16 v[22:25], v[134:137], v[190:193], v[22:25]
	v_mfma_f32_16x16x32_bf16 v[38:41], v[142:145], v[190:193], v[38:41]
	s_setprio 0
	s_setprio 1
	v_mfma_f32_16x16x32_bf16 v[34:37], v[146:149], v[162:165], v[34:37]
	v_mfma_f32_16x16x32_bf16 v[30:33], v[154:157], v[162:165], v[30:33]
	v_mfma_f32_16x16x32_bf16 v[42:45], v[146:149], v[166:169], v[42:45]
	v_mfma_f32_16x16x32_bf16 v[46:49], v[154:157], v[166:169], v[46:49]
	v_mfma_f32_16x16x32_bf16 v[50:53], v[146:149], v[178:181], v[50:53]
	v_mfma_f32_16x16x32_bf16 v[54:57], v[154:157], v[178:181], v[54:57]
	v_mfma_f32_16x16x32_bf16 v[58:61], v[146:149], v[182:185], v[58:61]
	v_mfma_f32_16x16x32_bf16 v[62:65], v[154:157], v[182:185], v[62:65]
	v_mfma_f32_16x16x32_bf16 v[34:37], v[150:153], v[170:173], v[34:37]
	v_mfma_f32_16x16x32_bf16 v[30:33], v[158:161], v[170:173], v[30:33]
	v_mfma_f32_16x16x32_bf16 v[42:45], v[150:153], v[174:177], v[42:45]
	v_mfma_f32_16x16x32_bf16 v[46:49], v[158:161], v[174:177], v[46:49]
	v_mfma_f32_16x16x32_bf16 v[50:53], v[150:153], v[186:189], v[50:53]
	v_mfma_f32_16x16x32_bf16 v[54:57], v[158:161], v[186:189], v[54:57]
	v_mfma_f32_16x16x32_bf16 v[58:61], v[150:153], v[190:193], v[58:61]
	v_mfma_f32_16x16x32_bf16 v[62:65], v[158:161], v[190:193], v[62:65]
	s_setprio 0
	s_add_i32 s4, s4, 2
	s_addk_i32 s5, 0x100
	s_cmp_gt_u32 s4, 13
	s_cbranch_scc0 my_rot_841
	s_barrier
	s_and_b64 vcc, exec, s[16:17]
	s_cbranch_vccz .LBB0_844
	s_barrier

.LBB0_1121:
	s_lshl_b32 s51, s19, 19
	v_cmp_lt_i64_e32 vcc, s[4:5], v[228:229]
	s_add_i32 s51, s51, 0x4000000
	s_and_b64 s[4:5], vcc, exec
	s_cselect_b32 s4, s51, s31
	s_lshl_b32 s52, s18, 19
	s_add_i32 s52, s52, 0x1a00000
	s_and_b64 s[54:55], vcc, exec
	s_cselect_b32 s5, s52, s26
	s_mov_b32 s33, 0
	s_movk_i32 s53, 0xfa00
	s_branch .LBB0_1122
my_rot_1122:
	s_barrier
.LBB0_1122:
	ds_read_b128 v[130:133], v240
	ds_read_b128 v[134:137], v241
	ds_read_b128 v[138:141], v242
	ds_read_b128 v[142:145], v243
	ds_read_b128 v[146:149], v244
	ds_read_b128 v[150:153], v245
	ds_read_b128 v[154:157], v246
	ds_read_b128 v[158:161], v247
	s_add_i32 s8, s31, s53
	s_add_i32 s55, s26, s53
	s_add_i32 s54, s8, 0x800
	s_addk_i32 s55, 0x800
	s_cmp_eq_u32 s53, 0
	s_cselect_b32 s56, s4, s54
	s_cselect_b32 s55, s5, s55
	s_add_i32 s54, s56, 0x80
	s_add_i32 s57, s8, 0x40780
	s_mov_b32 s8, s70
	s_mov_b32 m0, s44
	ds_read_b128 v[162:165], v248
	ds_read_b128 v[166:169], v248 offset:2048
	ds_read_b128 v[170:173], v249
	ds_read_b128 v[174:177], v249 offset:2048
	ds_read_b128 v[178:181], v248 offset:4096
	ds_read_b128 v[182:185], v248 offset:6144
	ds_read_b128 v[186:189], v249 offset:4096
	ds_read_b128 v[190:193], v249 offset:6144
	buffer_load_dwordx4 v1, s[8:11], s57 offen lds
	s_mov_b32 m0, s45
	s_nop 0
	buffer_load_dwordx4 v234, s[8:11], s57 offen lds
	s_waitcnt vmcnt(8)
	s_waitcnt lgkmcnt(0)
	s_barrier
	s_setprio 1
	s_waitcnt lgkmcnt(7)
	v_mfma_f32_16x16x32_bf16 v[126:129], v[130:133], v[162:165], v[126:129]
	v_mfma_f32_16x16x32_bf16 v[122:125], v[138:141], v[162:165], v[122:125]
	s_waitcnt lgkmcnt(6)
	v_mfma_f32_16x16x32_bf16 v[118:121], v[130:133], v[166:169], v[118:121]
	v_mfma_f32_16x16x32_bf16 v[114:117], v[138:141], v[166:169], v[114:117]
	s_waitcnt lgkmcnt(3)
	v_mfma_f32_16x16x32_bf16 v[110:113], v[130:133], v[178:181], v[110:113]
	v_mfma_f32_16x16x32_bf16 v[106:109], v[138:141], v[178:181], v[106:109]
	s_waitcnt lgkmcnt(2)
	v_mfma_f32_16x16x32_bf16 v[102:105], v[130:133], v[182:185], v[102:105]
	v_mfma_f32_16x16x32_bf16 v[98:101], v[138:141], v[182:185], v[98:101]
	v_mfma_f32_16x16x32_bf16 v[126:129], v[134:137], v[170:173], v[126:129]
	v_mfma_f32_16x16x32_bf16 v[122:125], v[142:145], v[170:173], v[122:125]
	v_mfma_f32_16x16x32_bf16 v[118:121], v[134:137], v[174:177], v[118:121]
	v_mfma_f32_16x16x32_bf16 v[114:117], v[142:145], v[174:177], v[114:117]
	s_waitcnt lgkmcnt(1)
	v_mfma_f32_16x16x32_bf16 v[110:113], v[134:137], v[186:189], v[110:113]
	v_mfma_f32_16x16x32_bf16 v[106:109], v[142:145], v[186:189], v[106:109]
	s_waitcnt lgkmcnt(0)
	v_mfma_f32_16x16x32_bf16 v[102:105], v[134:137], v[190:193], v[102:105]
	v_mfma_f32_16x16x32_bf16 v[98:101], v[142:145], v[190:193], v[98:101]
	s_setprio 0
	s_setprio 1
	v_mfma_f32_16x16x32_bf16 v[94:97], v[146:149], v[162:165], v[94:97]
	v_mfma_f32_16x16x32_bf16 v[90:93], v[154:157], v[162:165], v[90:93]
	v_mfma_f32_16x16x32_bf16 v[86:89], v[146:149], v[166:169], v[86:89]
	v_mfma_f32_16x16x32_bf16 v[82:85], v[154:157], v[166:169], v[82:85]
	v_mfma_f32_16x16x32_bf16 v[78:81], v[146:149], v[178:181], v[78:81]
	v_mfma_f32_16x16x32_bf16 v[74:77], v[154:157], v[178:181], v[74:77]
	v_mfma_f32_16x16x32_bf16 v[70:73], v[146:149], v[182:185], v[70:73]
	v_mfma_f32_16x16x32_bf16 v[66:69], v[154:157], v[182:185], v[66:69]
	v_mfma_f32_16x16x32_bf16 v[94:97], v[150:153], v[170:173], v[94:97]
	v_mfma_f32_16x16x32_bf16 v[90:93], v[158:161], v[170:173], v[90:93]
	v_mfma_f32_16x16x32_bf16 v[86:89], v[150:153], v[174:177], v[86:89]
	v_mfma_f32_16x16x32_bf16 v[82:85], v[158:161], v[174:177], v[82:85]
	v_mfma_f32_16x16x32_bf16 v[78:81], v[150:153], v[186:189], v[78:81]
	v_mfma_f32_16x16x32_bf16 v[74:77], v[158:161], v[186:189], v[74:77]
	v_mfma_f32_16x16x32_bf16 v[70:73], v[150:153], v[190:193], v[70:73]
	v_mfma_f32_16x16x32_bf16 v[66:69], v[158:161], v[190:193], v[66:69]
	s_setprio 0
	s_barrier
	s_mov_b32 m0, s23
	ds_read_b128 v[162:165], v248 offset:16384
	ds_read_b128 v[166:169], v248 offset:18432
	ds_read_b128 v[170:173], v249 offset:16384
	ds_read_b128 v[174:177], v249 offset:18432
	ds_read_b128 v[178:181], v248 offset:20480
	ds_read_b128 v[182:185], v248 offset:22528
	ds_read_b128 v[186:189], v249 offset:20480
	ds_read_b128 v[190:193], v249 offset:22528
	buffer_load_dwordx4 v233, s[8:11], s55 offen lds
	s_mov_b32 m0, s24
	s_add_i32 s57, s55, 0x40000
	buffer_load_dwordx4 v235, s[8:11], s55 offen lds
	s_mov_b32 m0, s25
	s_nop 0
	buffer_load_dwordx4 v233, s[8:11], s57 offen lds
	s_mov_b32 m0, s27
	s_nop 0
	buffer_load_dwordx4 v235, s[8:11], s57 offen lds
	s_mov_b32 m0, s22
	s_nop 0
	buffer_load_dwordx4 v1, s[8:11], s56 offen lds
	s_mov_b32 m0, s28
	s_nop 0
	buffer_load_dwordx4 v234, s[8:11], s56 offen lds
	s_waitcnt vmcnt(8)
	s_waitcnt lgkmcnt(0)
	s_barrier
	s_setprio 1
	s_waitcnt lgkmcnt(7)
	v_mfma_f32_16x16x32_bf16 v[62:65], v[130:133], v[162:165], v[62:65]
	v_mfma_f32_16x16x32_bf16 v[58:61], v[138:141], v[162:165], v[58:61]
	s_waitcnt lgkmcnt(6)
	v_mfma_f32_16x16x32_bf16 v[54:57], v[130:133], v[166:169], v[54:57]
	v_mfma_f32_16x16x32_bf16 v[50:53], v[138:141], v[166:169], v[50:53]
	s_waitcnt lgkmcnt(3)
	v_mfma_f32_16x16x32_bf16 v[46:49], v[130:133], v[178:181], v[46:49]
	v_mfma_f32_16x16x32_bf16 v[42:45], v[138:141], v[178:181], v[42:45]
	s_waitcnt lgkmcnt(2)
	v_mfma_f32_16x16x32_bf16 v[38:41], v[130:133], v[182:185], v[38:41]
	v_mfma_f32_16x16x32_bf16 v[34:37], v[138:141], v[182:185], v[34:37]
	v_mfma_f32_16x16x32_bf16 v[62:65], v[134:137], v[170:173], v[62:65]
	v_mfma_f32_16x16x32_bf16 v[58:61], v[142:145], v[170:173], v[58:61]
	v_mfma_f32_16x16x32_bf16 v[54:57], v[134:137], v[174:177], v[54:57]
	v_mfma_f32_16x16x32_bf16 v[50:53], v[142:145], v[174:177], v[50:53]
	s_waitcnt lgkmcnt(1)
	v_mfma_f32_16x16x32_bf16 v[46:49], v[134:137], v[186:189], v[46:49]
	v_mfma_f32_16x16x32_bf16 v[42:45], v[142:145], v[186:189], v[42:45]
	s_waitcnt lgkmcnt(0)
	v_mfma_f32_16x16x32_bf16 v[38:41], v[134:137], v[190:193], v[38:41]
	v_mfma_f32_16x16x32_bf16 v[34:37], v[142:145], v[190:193], v[34:37]
	s_setprio 0
	s_setprio 1
	v_mfma_f32_16x16x32_bf16 v[30:33], v[146:149], v[162:165], v[30:33]
	v_mfma_f32_16x16x32_bf16 v[26:29], v[154:157], v[162:165], v[26:29]
	v_mfma_f32_16x16x32_bf16 v[22:25], v[146:149], v[166:169], v[22:25]
	v_mfma_f32_16x16x32_bf16 v[18:21], v[154:157], v[166:169], v[18:21]
	v_mfma_f32_16x16x32_bf16 v[14:17], v[146:149], v[178:181], v[14:17]
	v_mfma_f32_16x16x32_bf16 v[10:13], v[154:157], v[178:181], v[10:13]
	v_mfma_f32_16x16x32_bf16 v[6:9], v[146:149], v[182:185], v[6:9]
	v_mfma_f32_16x16x32_bf16 v[2:5], v[154:157], v[182:185], v[2:5]
	v_mfma_f32_16x16x32_bf16 v[30:33], v[150:153], v[170:173], v[30:33]
	v_mfma_f32_16x16x32_bf16 v[26:29], v[158:161], v[170:173], v[26:29]
	v_mfma_f32_16x16x32_bf16 v[22:25], v[150:153], v[174:177], v[22:25]
	v_mfma_f32_16x16x32_bf16 v[18:21], v[158:161], v[174:177], v[18:21]
	v_mfma_f32_16x16x32_bf16 v[14:17], v[150:153], v[186:189], v[14:17]
	v_mfma_f32_16x16x32_bf16 v[10:13], v[158:161], v[186:189], v[10:13]
	v_mfma_f32_16x16x32_bf16 v[6:9], v[150:153], v[190:193], v[6:9]
	v_mfma_f32_16x16x32_bf16 v[2:5], v[158:161], v[190:193], v[2:5]
	s_setprio 0
	s_barrier
	ds_read_b128 v[130:133], v194
	ds_read_b128 v[134:137], v195
	ds_read_b128 v[138:141], v196
	ds_read_b128 v[142:145], v197
	ds_read_b128 v[146:149], v198
	ds_read_b128 v[150:153], v199
	ds_read_b128 v[154:157], v200
	ds_read_b128 v[158:161], v201
	s_add_i32 s56, s56, 0x40000
	s_mov_b32 m0, s29
	ds_read_b128 v[162:165], v248 offset:32768
	ds_read_b128 v[166:169], v248 offset:34816
	ds_read_b128 v[170:173], v249 offset:32768
	ds_read_b128 v[174:177], v249 offset:34816
	ds_read_b128 v[178:181], v248 offset:36864
	ds_read_b128 v[182:185], v248 offset:38912
	ds_read_b128 v[186:189], v249 offset:36864
	ds_read_b128 v[190:193], v249 offset:38912
	buffer_load_dwordx4 v1, s[8:11], s56 offen lds
	s_mov_b32 m0, s30
	s_nop 0
	buffer_load_dwordx4 v234, s[8:11], s56 offen lds
	s_waitcnt vmcnt(8)
	s_waitcnt lgkmcnt(0)
	s_barrier
	s_setprio 1
	s_waitcnt lgkmcnt(7)
	v_mfma_f32_16x16x32_bf16 v[126:129], v[130:133], v[162:165], v[126:129]
	v_mfma_f32_16x16x32_bf16 v[122:125], v[138:141], v[162:165], v[122:125]
	s_waitcnt lgkmcnt(6)
	v_mfma_f32_16x16x32_bf16 v[118:121], v[130:133], v[166:169], v[118:121]
	v_mfma_f32_16x16x32_bf16 v[114:117], v[138:141], v[166:169], v[114:117]
	s_waitcnt lgkmcnt(3)
	v_mfma_f32_16x16x32_bf16 v[110:113], v[130:133], v[178:181], v[110:113]
	v_mfma_f32_16x16x32_bf16 v[106:109], v[138:141], v[178:181], v[106:109]
	s_waitcnt lgkmcnt(2)
	v_mfma_f32_16x16x32_bf16 v[102:105], v[130:133], v[182:185], v[102:105]
	v_mfma_f32_16x16x32_bf16 v[98:101], v[138:141], v[182:185], v[98:101]
	v_mfma_f32_16x16x32_bf16 v[126:129], v[134:137], v[170:173], v[126:129]
	v_mfma_f32_16x16x32_bf16 v[122:125], v[142:145], v[170:173], v[122:125]
	v_mfma_f32_16x16x32_bf16 v[118:121], v[134:137], v[174:177], v[118:121]
	v_mfma_f32_16x16x32_bf16 v[114:117], v[142:145], v[174:177], v[114:117]
	s_waitcnt lgkmcnt(1)
	v_mfma_f32_16x16x32_bf16 v[110:113], v[134:137], v[186:189], v[110:113]
	v_mfma_f32_16x16x32_bf16 v[106:109], v[142:145], v[186:189], v[106:109]
	s_waitcnt lgkmcnt(0)
	v_mfma_f32_16x16x32_bf16 v[102:105], v[134:137], v[190:193], v[102:105]
	v_mfma_f32_16x16x32_bf16 v[98:101], v[142:145], v[190:193], v[98:101]
	s_setprio 0
	s_setprio 1
	v_mfma_f32_16x16x32_bf16 v[94:97], v[146:149], v[162:165], v[94:97]
	v_mfma_f32_16x16x32_bf16 v[90:93], v[154:157], v[162:165], v[90:93]
	v_mfma_f32_16x16x32_bf16 v[86:89], v[146:149], v[166:169], v[86:89]
	v_mfma_f32_16x16x32_bf16 v[82:85], v[154:157], v[166:169], v[82:85]
	v_mfma_f32_16x16x32_bf16 v[78:81], v[146:149], v[178:181], v[78:81]
	v_mfma_f32_16x16x32_bf16 v[74:77], v[154:157], v[178:181], v[74:77]
	v_mfma_f32_16x16x32_bf16 v[70:73], v[146:149], v[182:185], v[70:73]
	v_mfma_f32_16x16x32_bf16 v[66:69], v[154:157], v[182:185], v[66:69]
	v_mfma_f32_16x16x32_bf16 v[94:97], v[150:153], v[170:173], v[94:97]
	v_mfma_f32_16x16x32_bf16 v[90:93], v[158:161], v[170:173], v[90:93]
	v_mfma_f32_16x16x32_bf16 v[86:89], v[150:153], v[174:177], v[86:89]
	v_mfma_f32_16x16x32_bf16 v[82:85], v[158:161], v[174:177], v[82:85]
	v_mfma_f32_16x16x32_bf16 v[78:81], v[150:153], v[186:189], v[78:81]
	v_mfma_f32_16x16x32_bf16 v[74:77], v[158:161], v[186:189], v[74:77]
	v_mfma_f32_16x16x32_bf16 v[70:73], v[150:153], v[190:193], v[70:73]
	v_mfma_f32_16x16x32_bf16 v[66:69], v[158:161], v[190:193], v[66:69]
	s_setprio 0
	s_barrier
	s_mov_b32 m0, s35
	s_add_i32 s56, s55, 0x80
	ds_read_b128 v[162:165], v248 offset:49152
	ds_read_b128 v[166:169], v248 offset:51200
	ds_read_b128 v[170:173], v249 offset:49152
	ds_read_b128 v[174:177], v249 offset:51200
	ds_read_b128 v[178:181], v248 offset:53248
	ds_read_b128 v[182:185], v248 offset:55296
	ds_read_b128 v[186:189], v249 offset:53248
	ds_read_b128 v[190:193], v249 offset:55296
	buffer_load_dwordx4 v233, s[8:11], s56 offen lds
	s_mov_b32 m0, s36
	s_add_i32 s55, s55, 0x40080
	buffer_load_dwordx4 v235, s[8:11], s56 offen lds
	s_mov_b32 m0, s39
	s_nop 0
	buffer_load_dwordx4 v233, s[8:11], s55 offen lds
	s_mov_b32 m0, s41
	s_nop 0
	buffer_load_dwordx4 v235, s[8:11], s55 offen lds
	s_mov_b32 m0, s37
	s_nop 0
	buffer_load_dwordx4 v1, s[8:11], s54 offen lds
	s_mov_b32 m0, s38
	s_nop 0
	buffer_load_dwordx4 v234, s[8:11], s54 offen lds
	s_waitcnt vmcnt(8)
	s_waitcnt lgkmcnt(0)
	s_barrier
	s_setprio 1
	s_waitcnt lgkmcnt(7)
	v_mfma_f32_16x16x32_bf16 v[62:65], v[130:133], v[162:165], v[62:65]
	v_mfma_f32_16x16x32_bf16 v[58:61], v[138:141], v[162:165], v[58:61]
	s_waitcnt lgkmcnt(6)
	v_mfma_f32_16x16x32_bf16 v[54:57], v[130:133], v[166:169], v[54:57]
	v_mfma_f32_16x16x32_bf16 v[50:53], v[138:141], v[166:169], v[50:53]
	s_waitcnt lgkmcnt(3)
	v_mfma_f32_16x16x32_bf16 v[46:49], v[130:133], v[178:181], v[46:49]
	v_mfma_f32_16x16x32_bf16 v[42:45], v[138:141], v[178:181], v[42:45]
	s_waitcnt lgkmcnt(2)
	v_mfma_f32_16x16x32_bf16 v[38:41], v[130:133], v[182:185], v[38:41]
	v_mfma_f32_16x16x32_bf16 v[34:37], v[138:141], v[182:185], v[34:37]
	v_mfma_f32_16x16x32_bf16 v[62:65], v[134:137], v[170:173], v[62:65]
	v_mfma_f32_16x16x32_bf16 v[58:61], v[142:145], v[170:173], v[58:61]
	v_mfma_f32_16x16x32_bf16 v[54:57], v[134:137], v[174:177], v[54:57]
	v_mfma_f32_16x16x32_bf16 v[50:53], v[142:145], v[174:177], v[50:53]
	s_waitcnt lgkmcnt(1)
	v_mfma_f32_16x16x32_bf16 v[46:49], v[134:137], v[186:189], v[46:49]
	v_mfma_f32_16x16x32_bf16 v[42:45], v[142:145], v[186:189], v[42:45]
	s_waitcnt lgkmcnt(0)
	v_mfma_f32_16x16x32_bf16 v[38:41], v[134:137], v[190:193], v[38:41]
	v_mfma_f32_16x16x32_bf16 v[34:37], v[142:145], v[190:193], v[34:37]
	s_setprio 0
	s_setprio 1
	v_mfma_f32_16x16x32_bf16 v[30:33], v[146:149], v[162:165], v[30:33]
	v_mfma_f32_16x16x32_bf16 v[26:29], v[154:157], v[162:165], v[26:29]
	v_mfma_f32_16x16x32_bf16 v[22:25], v[146:149], v[166:169], v[22:25]
	v_mfma_f32_16x16x32_bf16 v[18:21], v[154:157], v[166:169], v[18:21]
	v_mfma_f32_16x16x32_bf16 v[14:17], v[146:149], v[178:181], v[14:17]
	v_mfma_f32_16x16x32_bf16 v[10:13], v[154:157], v[178:181], v[10:13]
	v_mfma_f32_16x16x32_bf16 v[6:9], v[146:149], v[182:185], v[6:9]
	v_mfma_f32_16x16x32_bf16 v[2:5], v[154:157], v[182:185], v[2:5]
	v_mfma_f32_16x16x32_bf16 v[30:33], v[150:153], v[170:173], v[30:33]
	v_mfma_f32_16x16x32_bf16 v[26:29], v[158:161], v[170:173], v[26:29]
	v_mfma_f32_16x16x32_bf16 v[22:25], v[150:153], v[174:177], v[22:25]
	v_mfma_f32_16x16x32_bf16 v[18:21], v[158:161], v[174:177], v[18:21]
	v_mfma_f32_16x16x32_bf16 v[14:17], v[150:153], v[186:189], v[14:17]
	v_mfma_f32_16x16x32_bf16 v[10:13], v[158:161], v[186:189], v[10:13]
	v_mfma_f32_16x16x32_bf16 v[6:9], v[150:153], v[190:193], v[6:9]
	v_mfma_f32_16x16x32_bf16 v[2:5], v[158:161], v[190:193], v[2:5]
	s_setprio 0
	s_add_i32 s33, s33, 2
	s_addk_i32 s53, 0x100
	s_cmp_gt_u32 s33, 13
	s_cbranch_scc0 my_rot_1122
	s_barrier
	s_and_b64 vcc, exec, s[16:17]
	s_cbranch_vccz .LBB0_1125
	s_barrier

.LBB0_1250:
	s_lshl_b32 s83, s81, 21
	v_cmp_lt_i64_e32 vcc, s[0:1], v[228:229]
	s_add_i32 s83, s83, 0xc000000
	s_and_b64 s[0:1], vcc, exec
	s_cselect_b32 s0, s83, s51
	s_lshl_b32 s84, s80, 21
	s_add_i32 s84, s84, 0x2200000
	s_and_b64 s[4:5], vcc, exec
	s_cselect_b32 s1, s84, s46
	s_mov_b32 s4, 0
	s_movk_i32 s5, 0xe200
	s_branch .LBB0_1251
my_rot_1251:
	s_barrier
.LBB0_1251:
	ds_read_b128 v[130:133], v239
	ds_read_b128 v[134:137], v240
	ds_read_b128 v[138:141], v241
	ds_read_b128 v[142:145], v242
	ds_read_b128 v[146:149], v243
	ds_read_b128 v[150:153], v244
	ds_read_b128 v[154:157], v245
	ds_read_b128 v[158:161], v246
	s_add_i32 s8, s51, s5
	s_add_i32 s31, s46, s5
	s_add_i32 s30, s8, 0x2000
	s_addk_i32 s31, 0x2000
	s_cmp_eq_u32 s5, 0
	s_cselect_b32 s33, s0, s30
	s_cselect_b32 s31, s1, s31
	s_add_i32 s30, s33, 0x80
	s_add_i32 s34, s8, 0x101f80
	s_mov_b32 s8, s70
	s_mov_b32 m0, s61
	ds_read_b128 v[162:165], v247
	ds_read_b128 v[166:169], v247 offset:2048
	ds_read_b128 v[170:173], v248
	ds_read_b128 v[174:177], v248 offset:2048
	ds_read_b128 v[178:181], v247 offset:4096
	ds_read_b128 v[182:185], v247 offset:6144
	ds_read_b128 v[186:189], v248 offset:4096
	ds_read_b128 v[190:193], v248 offset:6144
	buffer_load_dwordx4 v230, s[8:11], s34 offen lds
	s_mov_b32 m0, s64
	s_nop 0
	buffer_load_dwordx4 v233, s[8:11], s34 offen lds
	s_waitcnt vmcnt(8)
	s_waitcnt lgkmcnt(0)
	s_barrier
	s_setprio 1
	s_waitcnt lgkmcnt(7)
	v_mfma_f32_16x16x32_bf16 v[74:77], v[130:133], v[162:165], v[74:77]
	v_mfma_f32_16x16x32_bf16 v[70:73], v[138:141], v[162:165], v[70:73]
	s_waitcnt lgkmcnt(6)
	v_mfma_f32_16x16x32_bf16 v[66:69], v[130:133], v[166:169], v[66:69]
	v_mfma_f32_16x16x32_bf16 v[82:85], v[138:141], v[166:169], v[82:85]
	s_waitcnt lgkmcnt(3)
	v_mfma_f32_16x16x32_bf16 v[78:81], v[130:133], v[178:181], v[78:81]
	v_mfma_f32_16x16x32_bf16 v[90:93], v[138:141], v[178:181], v[90:93]
	s_waitcnt lgkmcnt(2)
	v_mfma_f32_16x16x32_bf16 v[86:89], v[130:133], v[182:185], v[86:89]
	v_mfma_f32_16x16x32_bf16 v[102:105], v[138:141], v[182:185], v[102:105]
	v_mfma_f32_16x16x32_bf16 v[74:77], v[134:137], v[170:173], v[74:77]
	v_mfma_f32_16x16x32_bf16 v[70:73], v[142:145], v[170:173], v[70:73]
	v_mfma_f32_16x16x32_bf16 v[66:69], v[134:137], v[174:177], v[66:69]
	v_mfma_f32_16x16x32_bf16 v[82:85], v[142:145], v[174:177], v[82:85]
	s_waitcnt lgkmcnt(1)
	v_mfma_f32_16x16x32_bf16 v[78:81], v[134:137], v[186:189], v[78:81]
	v_mfma_f32_16x16x32_bf16 v[90:93], v[142:145], v[186:189], v[90:93]
	s_waitcnt lgkmcnt(0)
	v_mfma_f32_16x16x32_bf16 v[86:89], v[134:137], v[190:193], v[86:89]
	v_mfma_f32_16x16x32_bf16 v[102:105], v[142:145], v[190:193], v[102:105]
	s_setprio 0
	s_setprio 1
	v_mfma_f32_16x16x32_bf16 v[98:101], v[146:149], v[162:165], v[98:101]
	v_mfma_f32_16x16x32_bf16 v[94:97], v[154:157], v[162:165], v[94:97]
	v_mfma_f32_16x16x32_bf16 v[106:109], v[146:149], v[166:169], v[106:109]
	v_mfma_f32_16x16x32_bf16 v[110:113], v[154:157], v[166:169], v[110:113]
	v_mfma_f32_16x16x32_bf16 v[114:117], v[146:149], v[178:181], v[114:117]
	v_mfma_f32_16x16x32_bf16 v[118:121], v[154:157], v[178:181], v[118:121]
	v_mfma_f32_16x16x32_bf16 v[122:125], v[146:149], v[182:185], v[122:125]
	v_mfma_f32_16x16x32_bf16 v[126:129], v[154:157], v[182:185], v[126:129]
	v_mfma_f32_16x16x32_bf16 v[98:101], v[150:153], v[170:173], v[98:101]
	v_mfma_f32_16x16x32_bf16 v[94:97], v[158:161], v[170:173], v[94:97]
	v_mfma_f32_16x16x32_bf16 v[106:109], v[150:153], v[174:177], v[106:109]
	v_mfma_f32_16x16x32_bf16 v[110:113], v[158:161], v[174:177], v[110:113]
	v_mfma_f32_16x16x32_bf16 v[114:117], v[150:153], v[186:189], v[114:117]
	v_mfma_f32_16x16x32_bf16 v[118:121], v[158:161], v[186:189], v[118:121]
	v_mfma_f32_16x16x32_bf16 v[122:125], v[150:153], v[190:193], v[122:125]
	v_mfma_f32_16x16x32_bf16 v[126:129], v[158:161], v[190:193], v[126:129]
	s_setprio 0
	s_barrier
	s_mov_b32 m0, s43
	ds_read_b128 v[162:165], v247 offset:16384
	ds_read_b128 v[166:169], v247 offset:18432
	ds_read_b128 v[170:173], v248 offset:16384
	ds_read_b128 v[174:177], v248 offset:18432
	ds_read_b128 v[178:181], v247 offset:20480
	ds_read_b128 v[182:185], v247 offset:22528
	ds_read_b128 v[186:189], v248 offset:20480
	ds_read_b128 v[190:193], v248 offset:22528
	buffer_load_dwordx4 v231, s[8:11], s31 offen lds
	s_mov_b32 m0, s44
	s_add_i32 s34, s31, 0x100000
	buffer_load_dwordx4 v234, s[8:11], s31 offen lds
	s_mov_b32 m0, s45
	s_nop 0
	buffer_load_dwordx4 v231, s[8:11], s34 offen lds
	s_mov_b32 m0, s47
	s_nop 0
	buffer_load_dwordx4 v234, s[8:11], s34 offen lds
	s_mov_b32 m0, s42
	s_nop 0
	buffer_load_dwordx4 v230, s[8:11], s33 offen lds
	s_mov_b32 m0, s48
	s_nop 0
	buffer_load_dwordx4 v233, s[8:11], s33 offen lds
	s_waitcnt vmcnt(8)
	s_waitcnt lgkmcnt(0)
	s_barrier
	s_setprio 1
	s_waitcnt lgkmcnt(7)
	v_mfma_f32_16x16x32_bf16 v[10:13], v[130:133], v[162:165], v[10:13]
	v_mfma_f32_16x16x32_bf16 v[6:9], v[138:141], v[162:165], v[6:9]
	s_waitcnt lgkmcnt(6)
	v_mfma_f32_16x16x32_bf16 v[0:3], v[130:133], v[166:169], v[2:5]
	v_mfma_f32_16x16x32_bf16 v[18:21], v[138:141], v[166:169], v[18:21]
	s_waitcnt lgkmcnt(3)
	v_mfma_f32_16x16x32_bf16 v[14:17], v[130:133], v[178:181], v[14:17]
	v_mfma_f32_16x16x32_bf16 v[26:29], v[138:141], v[178:181], v[26:29]
	s_waitcnt lgkmcnt(2)
	v_mfma_f32_16x16x32_bf16 v[22:25], v[130:133], v[182:185], v[22:25]
	v_mfma_f32_16x16x32_bf16 v[38:41], v[138:141], v[182:185], v[38:41]
	v_mfma_f32_16x16x32_bf16 v[10:13], v[134:137], v[170:173], v[10:13]
	v_mfma_f32_16x16x32_bf16 v[6:9], v[142:145], v[170:173], v[6:9]
	v_mfma_f32_16x16x32_bf16 v[0:3], v[134:137], v[174:177], v[0:3]
	v_mfma_f32_16x16x32_bf16 v[18:21], v[142:145], v[174:177], v[18:21]
	s_waitcnt lgkmcnt(1)
	v_mfma_f32_16x16x32_bf16 v[14:17], v[134:137], v[186:189], v[14:17]
	v_mfma_f32_16x16x32_bf16 v[26:29], v[142:145], v[186:189], v[26:29]
	s_waitcnt lgkmcnt(0)
	v_mfma_f32_16x16x32_bf16 v[22:25], v[134:137], v[190:193], v[22:25]
	v_mfma_f32_16x16x32_bf16 v[38:41], v[142:145], v[190:193], v[38:41]
	s_setprio 0
	s_setprio 1
	v_mfma_f32_16x16x32_bf16 v[34:37], v[146:149], v[162:165], v[34:37]
	v_mfma_f32_16x16x32_bf16 v[30:33], v[154:157], v[162:165], v[30:33]
	v_mfma_f32_16x16x32_bf16 v[42:45], v[146:149], v[166:169], v[42:45]
	v_mfma_f32_16x16x32_bf16 v[46:49], v[154:157], v[166:169], v[46:49]
	v_mfma_f32_16x16x32_bf16 v[50:53], v[146:149], v[178:181], v[50:53]
	v_mfma_f32_16x16x32_bf16 v[54:57], v[154:157], v[178:181], v[54:57]
	v_mfma_f32_16x16x32_bf16 v[58:61], v[146:149], v[182:185], v[58:61]
	v_mfma_f32_16x16x32_bf16 v[62:65], v[154:157], v[182:185], v[62:65]
	v_mfma_f32_16x16x32_bf16 v[34:37], v[150:153], v[170:173], v[34:37]
	v_mfma_f32_16x16x32_bf16 v[30:33], v[158:161], v[170:173], v[30:33]
	v_mfma_f32_16x16x32_bf16 v[42:45], v[150:153], v[174:177], v[42:45]
	v_mfma_f32_16x16x32_bf16 v[46:49], v[158:161], v[174:177], v[46:49]
	v_mfma_f32_16x16x32_bf16 v[50:53], v[150:153], v[186:189], v[50:53]
	v_mfma_f32_16x16x32_bf16 v[54:57], v[158:161], v[186:189], v[54:57]
	v_mfma_f32_16x16x32_bf16 v[58:61], v[150:153], v[190:193], v[58:61]
	v_mfma_f32_16x16x32_bf16 v[62:65], v[158:161], v[190:193], v[62:65]
	s_setprio 0
	s_barrier
	ds_read_b128 v[130:133], v194
	ds_read_b128 v[134:137], v195
	ds_read_b128 v[138:141], v196
	ds_read_b128 v[142:145], v197
	ds_read_b128 v[146:149], v198
	ds_read_b128 v[150:153], v199
	ds_read_b128 v[154:157], v200
	ds_read_b128 v[158:161], v201
	s_add_i32 s33, s33, 0x100000
	s_mov_b32 m0, s49
	ds_read_b128 v[162:165], v247 offset:32768
	ds_read_b128 v[166:169], v247 offset:34816
	ds_read_b128 v[170:173], v248 offset:32768
	ds_read_b128 v[174:177], v248 offset:34816
	ds_read_b128 v[178:181], v247 offset:36864
	ds_read_b128 v[182:185], v247 offset:38912
	ds_read_b128 v[186:189], v248 offset:36864
	ds_read_b128 v[190:193], v248 offset:38912
	buffer_load_dwordx4 v230, s[8:11], s33 offen lds
	s_mov_b32 m0, s50
	s_nop 0
	buffer_load_dwordx4 v233, s[8:11], s33 offen lds
	s_waitcnt vmcnt(8)
	s_waitcnt lgkmcnt(0)
	s_barrier
	s_setprio 1
	s_waitcnt lgkmcnt(7)
	v_mfma_f32_16x16x32_bf16 v[74:77], v[130:133], v[162:165], v[74:77]
	v_mfma_f32_16x16x32_bf16 v[70:73], v[138:141], v[162:165], v[70:73]
	s_waitcnt lgkmcnt(6)
	v_mfma_f32_16x16x32_bf16 v[66:69], v[130:133], v[166:169], v[66:69]
	v_mfma_f32_16x16x32_bf16 v[82:85], v[138:141], v[166:169], v[82:85]
	s_waitcnt lgkmcnt(3)
	v_mfma_f32_16x16x32_bf16 v[78:81], v[130:133], v[178:181], v[78:81]
	v_mfma_f32_16x16x32_bf16 v[90:93], v[138:141], v[178:181], v[90:93]
	s_waitcnt lgkmcnt(2)
	v_mfma_f32_16x16x32_bf16 v[86:89], v[130:133], v[182:185], v[86:89]
	v_mfma_f32_16x16x32_bf16 v[102:105], v[138:141], v[182:185], v[102:105]
	v_mfma_f32_16x16x32_bf16 v[74:77], v[134:137], v[170:173], v[74:77]
	v_mfma_f32_16x16x32_bf16 v[70:73], v[142:145], v[170:173], v[70:73]
	v_mfma_f32_16x16x32_bf16 v[66:69], v[134:137], v[174:177], v[66:69]
	v_mfma_f32_16x16x32_bf16 v[82:85], v[142:145], v[174:177], v[82:85]
	s_waitcnt lgkmcnt(1)
	v_mfma_f32_16x16x32_bf16 v[78:81], v[134:137], v[186:189], v[78:81]
	v_mfma_f32_16x16x32_bf16 v[90:93], v[142:145], v[186:189], v[90:93]
	s_waitcnt lgkmcnt(0)
	v_mfma_f32_16x16x32_bf16 v[86:89], v[134:137], v[190:193], v[86:89]
	v_mfma_f32_16x16x32_bf16 v[102:105], v[142:145], v[190:193], v[102:105]
	s_setprio 0
	s_setprio 1
	v_mfma_f32_16x16x32_bf16 v[98:101], v[146:149], v[162:165], v[98:101]
	v_mfma_f32_16x16x32_bf16 v[94:97], v[154:157], v[162:165], v[94:97]
	v_mfma_f32_16x16x32_bf16 v[106:109], v[146:149], v[166:169], v[106:109]
	v_mfma_f32_16x16x32_bf16 v[110:113], v[154:157], v[166:169], v[110:113]
	v_mfma_f32_16x16x32_bf16 v[114:117], v[146:149], v[178:181], v[114:117]
	v_mfma_f32_16x16x32_bf16 v[118:121], v[154:157], v[178:181], v[118:121]
	v_mfma_f32_16x16x32_bf16 v[122:125], v[146:149], v[182:185], v[122:125]
	v_mfma_f32_16x16x32_bf16 v[126:129], v[154:157], v[182:185], v[126:129]
	v_mfma_f32_16x16x32_bf16 v[98:101], v[150:153], v[170:173], v[98:101]
	v_mfma_f32_16x16x32_bf16 v[94:97], v[158:161], v[170:173], v[94:97]
	v_mfma_f32_16x16x32_bf16 v[106:109], v[150:153], v[174:177], v[106:109]
	v_mfma_f32_16x16x32_bf16 v[110:113], v[158:161], v[174:177], v[110:113]
	v_mfma_f32_16x16x32_bf16 v[114:117], v[150:153], v[186:189], v[114:117]
	v_mfma_f32_16x16x32_bf16 v[118:121], v[158:161], v[186:189], v[118:121]
	v_mfma_f32_16x16x32_bf16 v[122:125], v[150:153], v[190:193], v[122:125]
	v_mfma_f32_16x16x32_bf16 v[126:129], v[158:161], v[190:193], v[126:129]
	s_setprio 0
	s_barrier
	s_mov_b32 m0, s53
	s_add_i32 s33, s31, 0x80
	ds_read_b128 v[162:165], v247 offset:49152
	ds_read_b128 v[166:169], v247 offset:51200
	ds_read_b128 v[170:173], v248 offset:49152
	ds_read_b128 v[174:177], v248 offset:51200
	ds_read_b128 v[178:181], v247 offset:53248
	ds_read_b128 v[182:185], v247 offset:55296
	ds_read_b128 v[186:189], v248 offset:53248
	ds_read_b128 v[190:193], v248 offset:55296
	buffer_load_dwordx4 v231, s[8:11], s33 offen lds
	s_mov_b32 m0, s54
	s_add_i32 s31, s31, 0x100080
	buffer_load_dwordx4 v234, s[8:11], s33 offen lds
	s_mov_b32 m0, s57
	s_nop 0
	buffer_load_dwordx4 v231, s[8:11], s31 offen lds
	s_mov_b32 m0, s58
	s_nop 0
	buffer_load_dwordx4 v234, s[8:11], s31 offen lds
	s_mov_b32 m0, s55
	s_nop 0
	buffer_load_dwordx4 v230, s[8:11], s30 offen lds
	s_mov_b32 m0, s56
	s_nop 0
	buffer_load_dwordx4 v233, s[8:11], s30 offen lds
	s_waitcnt vmcnt(8)
	s_waitcnt lgkmcnt(0)
	s_barrier
	s_setprio 1
	s_waitcnt lgkmcnt(7)
	v_mfma_f32_16x16x32_bf16 v[10:13], v[130:133], v[162:165], v[10:13]
	v_mfma_f32_16x16x32_bf16 v[4:7], v[138:141], v[162:165], v[6:9]
	s_waitcnt lgkmcnt(6)
	v_mfma_f32_16x16x32_bf16 v[0:3], v[130:133], v[166:169], v[0:3]
	v_mfma_f32_16x16x32_bf16 v[18:21], v[138:141], v[166:169], v[18:21]
	s_waitcnt lgkmcnt(3)
	v_mfma_f32_16x16x32_bf16 v[14:17], v[130:133], v[178:181], v[14:17]
	v_mfma_f32_16x16x32_bf16 v[26:29], v[138:141], v[178:181], v[26:29]
	s_waitcnt lgkmcnt(2)
	v_mfma_f32_16x16x32_bf16 v[22:25], v[130:133], v[182:185], v[22:25]
	v_mfma_f32_16x16x32_bf16 v[38:41], v[138:141], v[182:185], v[38:41]
	v_mfma_f32_16x16x32_bf16 v[10:13], v[134:137], v[170:173], v[10:13]
	v_mfma_f32_16x16x32_bf16 v[6:9], v[142:145], v[170:173], v[4:7]
	v_mfma_f32_16x16x32_bf16 v[2:5], v[134:137], v[174:177], v[0:3]
	v_mfma_f32_16x16x32_bf16 v[18:21], v[142:145], v[174:177], v[18:21]
	s_waitcnt lgkmcnt(1)
	v_mfma_f32_16x16x32_bf16 v[14:17], v[134:137], v[186:189], v[14:17]
	v_mfma_f32_16x16x32_bf16 v[26:29], v[142:145], v[186:189], v[26:29]
	s_waitcnt lgkmcnt(0)
	v_mfma_f32_16x16x32_bf16 v[22:25], v[134:137], v[190:193], v[22:25]
	v_mfma_f32_16x16x32_bf16 v[38:41], v[142:145], v[190:193], v[38:41]
	s_setprio 0
	s_setprio 1
	v_mfma_f32_16x16x32_bf16 v[34:37], v[146:149], v[162:165], v[34:37]
	v_mfma_f32_16x16x32_bf16 v[30:33], v[154:157], v[162:165], v[30:33]
	v_mfma_f32_16x16x32_bf16 v[42:45], v[146:149], v[166:169], v[42:45]
	v_mfma_f32_16x16x32_bf16 v[46:49], v[154:157], v[166:169], v[46:49]
	v_mfma_f32_16x16x32_bf16 v[50:53], v[146:149], v[178:181], v[50:53]
	v_mfma_f32_16x16x32_bf16 v[54:57], v[154:157], v[178:181], v[54:57]
	v_mfma_f32_16x16x32_bf16 v[58:61], v[146:149], v[182:185], v[58:61]
	v_mfma_f32_16x16x32_bf16 v[62:65], v[154:157], v[182:185], v[62:65]
	v_mfma_f32_16x16x32_bf16 v[34:37], v[150:153], v[170:173], v[34:37]
	v_mfma_f32_16x16x32_bf16 v[30:33], v[158:161], v[170:173], v[30:33]
	v_mfma_f32_16x16x32_bf16 v[42:45], v[150:153], v[174:177], v[42:45]
	v_mfma_f32_16x16x32_bf16 v[46:49], v[158:161], v[174:177], v[46:49]
	v_mfma_f32_16x16x32_bf16 v[50:53], v[150:153], v[186:189], v[50:53]
	v_mfma_f32_16x16x32_bf16 v[54:57], v[158:161], v[186:189], v[54:57]
	v_mfma_f32_16x16x32_bf16 v[58:61], v[150:153], v[190:193], v[58:61]
	v_mfma_f32_16x16x32_bf16 v[62:65], v[158:161], v[190:193], v[62:65]
	s_setprio 0
	s_add_i32 s4, s4, 2
	s_addk_i32 s5, 0x100
	s_cmp_gt_u32 s4, 61
	s_cbranch_scc0 my_rot_1251
	s_barrier
	s_and_b64 vcc, exec, s[18:19]
	s_cbranch_vccz .LBB0_1254
	s_barrier
